# c14 + attention output stores nt + conv-to-gates barrier in the RG-LRU local pass removed (traffic stays inside one wave)
# baseline (speedup 1.0000x reference)
; DEVI float bflo(unsigned w) { return __uint_as_float(w << 16); }
; DEVI float bfhi(unsigned w) { return __uint_as_float(w & 0xffff0000u); }
; #define RNN_LOAD(j_) do { const int b_ = (j_) >> 7, t0_ = ((j_) & 127) * 128; _Pragma("unroll") for (int k = 0; k < 4; ++k) { const int s_ = t0_ + tok - 3 + k; \
;         const bf16_t* p_ = xr + ((size_t)b_ * SEQ + (s_ < 0 ? 0 : s_)) * DM + ch0 + cg4; xw[2 * k] = *(const u32x4*)p_; xw[2 * k + 1] = *(const u32x4*)(p_ + 8); } } while (0)
; DEVI void rnn_local_phase(const bf16_t* xr, const float* convw, const float* convb, const bf16_t* lruT, const float* ba, const float* bx, const float* lam,
;                           bf16_t* hloc, bf16_t* pcum, float* aggA, float* aggH, char* lds, int wv) {
;     ...
;             for (int i = 0; i < 16; i += 4) { const f32x4 bb = *(const f32x4*)(cwL + 256 + cg4 + i); xc[i] = bb[0]; xc[i + 1] = bb[1]; xc[i + 2] = bb[2]; xc[i + 3] = bb[3]; }
; #pragma unroll
;             for (int k = 0; k < 4; ++k) { const float zf = (t0 + tok - 3 + k) >= 0 ? 1.f : 0.f; const u32x4 w0 = xw[2 * k], w1 = xw[2 * k + 1];
;                 const float xv[16] = {bflo(w0.x), bfhi(w0.x), bflo(w0.y), bfhi(w0.y), bflo(w0.z), bfhi(w0.z), bflo(w0.w), bfhi(w0.w), bflo(w1.x), bfhi(w1.x), bflo(w1.y), bfhi(w1.y), bflo(w1.z), bfhi(w1.z), bflo(w1.w), bfhi(w1.w)};
; #pragma unroll
;                 for (int i = 0; i < 16; i += 4) { const f32x4 cw = *(const f32x4*)(cwL + k * 64 + cg4 + i) * zf; xc[i] += cw[0] * xv[i]; xc[i + 1] += cw[1] * xv[i + 1]; xc[i + 2] += cw[2] * xv[i + 2]; xc[i + 3] += cw[3] * xv[i + 3]; } }
;             if (j + ns < 256) RNN_LOAD(j + ns);
; #pragma unroll
;             for (int i = 0; i < 16; ++i) xcf[tok * 65 + cg4 + i] = xc[i];
.LBB0_123:
	s_and_b32 s78, s60, 0x7f
	s_lshl_b32 s79, s78, 7
	v_add_u32_e32 v196, s79, v157
	v_cmp_lt_i32_e32 vcc, 2, v196
	v_and_b32_e32 v197, 0xffff0000, v62
	s_nop 0
	v_cndmask_b32_e64 v0, 0, 1.0, vcc
	v_cmp_lt_i32_e32 vcc, 1, v196
	s_waitcnt lgkmcnt(0)
	v_pk_mul_f32 v[144:145], v[144:145], v[0:1] op_sel_hi:[1,0]
	v_pk_mul_f32 v[142:143], v[142:143], v[0:1] op_sel_hi:[1,0]
	v_pk_mul_f32 v[140:141], v[140:141], v[0:1] op_sel_hi:[1,0]
	v_pk_mul_f32 v[138:139], v[138:139], v[0:1] op_sel_hi:[1,0]
	v_pk_mul_f32 v[136:137], v[0:1], v[136:137] op_sel_hi:[0,1]
	v_pk_mul_f32 v[134:135], v[0:1], v[134:135] op_sel_hi:[0,1]
	v_pk_mul_f32 v[132:133], v[0:1], v[132:133] op_sel_hi:[0,1]
	v_pk_mul_f32 v[130:131], v[0:1], v[130:131] op_sel_hi:[0,1]
	v_cndmask_b32_e64 v0, 0, 1.0, vcc
	v_cmp_lt_i32_e32 vcc, 0, v196
	v_pk_mul_f32 v[128:129], v[0:1], v[128:129] op_sel_hi:[0,1]
	v_pk_mul_f32 v[126:127], v[0:1], v[126:127] op_sel_hi:[0,1]
	v_pk_mul_f32 v[124:125], v[0:1], v[124:125] op_sel_hi:[0,1]
	v_pk_mul_f32 v[122:123], v[0:1], v[122:123] op_sel_hi:[0,1]
	v_pk_mul_f32 v[120:121], v[0:1], v[120:121] op_sel_hi:[0,1]
	v_pk_mul_f32 v[118:119], v[0:1], v[118:119] op_sel_hi:[0,1]
	v_pk_mul_f32 v[116:117], v[0:1], v[116:117] op_sel_hi:[0,1]
	v_pk_mul_f32 v[114:115], v[0:1], v[114:115] op_sel_hi:[0,1]
	v_cndmask_b32_e64 v0, 0, 1.0, vcc
	v_cmp_lt_i32_e32 vcc, -1, v196
	v_lshlrev_b32_e32 v196, 16, v62
	v_lshlrev_b32_e32 v62, 16, v63
	v_and_b32_e32 v63, 0xffff0000, v63
	v_pk_fma_f32 v[90:91], v[142:143], v[196:197], v[90:91]
	v_lshlrev_b32_e32 v142, 16, v58
	v_and_b32_e32 v143, 0xffff0000, v58
	v_pk_fma_f32 v[62:63], v[144:145], v[62:63], v[92:93]
	v_lshlrev_b32_e32 v58, 16, v59
	v_and_b32_e32 v59, 0xffff0000, v59
	v_pk_fma_f32 v[58:59], v[128:129], v[58:59], v[62:63]
	v_lshlrev_b32_e32 v62, 16, v64
	v_and_b32_e32 v63, 0xffff0000, v64
	v_pk_fma_f32 v[62:63], v[138:139], v[62:63], v[82:83]
	v_lshlrev_b32_e32 v82, 16, v60
	v_and_b32_e32 v83, 0xffff0000, v60
	v_pk_mul_f32 v[112:113], v[0:1], v[112:113] op_sel_hi:[0,1]
	v_pk_mul_f32 v[110:111], v[0:1], v[110:111] op_sel_hi:[0,1]
	v_pk_mul_f32 v[108:109], v[0:1], v[108:109] op_sel_hi:[0,1]
	v_pk_mul_f32 v[106:107], v[0:1], v[106:107] op_sel_hi:[0,1]
	v_pk_mul_f32 v[104:105], v[0:1], v[104:105] op_sel_hi:[0,1]
	v_pk_mul_f32 v[102:103], v[0:1], v[102:103] op_sel_hi:[0,1]
	v_pk_mul_f32 v[100:101], v[0:1], v[100:101] op_sel_hi:[0,1]
	v_pk_mul_f32 v[98:99], v[0:1], v[98:99] op_sel_hi:[0,1]
	v_cndmask_b32_e64 v0, 0, 1.0, vcc
	v_pk_fma_f32 v[90:91], v[126:127], v[142:143], v[90:91]
	v_lshlrev_b32_e32 v126, 16, v54
	v_and_b32_e32 v127, 0xffff0000, v54
	v_lshlrev_b32_e32 v54, 16, v55
	v_and_b32_e32 v55, 0xffff0000, v55
	v_pk_fma_f32 v[62:63], v[122:123], v[82:83], v[62:63]
	v_lshlrev_b32_e32 v82, 16, v56
	v_and_b32_e32 v83, 0xffff0000, v56
	v_pk_fma_f32 v[54:55], v[112:113], v[54:55], v[58:59]
	v_pk_mul_f32 v[58:59], v[0:1], v[86:87] op_sel_hi:[0,1]
	v_pk_fma_f32 v[62:63], v[106:107], v[82:83], v[62:63]
	v_lshlrev_b32_e32 v82, 16, v52
	v_and_b32_e32 v83, 0xffff0000, v52
	v_pk_fma_f32 v[58:59], v[58:59], v[82:83], v[62:63]
	v_lshlrev_b32_e32 v62, 16, v65
	v_and_b32_e32 v63, 0xffff0000, v65
	v_pk_fma_f32 v[62:63], v[140:141], v[62:63], v[84:85]
	v_lshlrev_b32_e32 v60, 16, v61
	v_and_b32_e32 v61, 0xffff0000, v61
	v_pk_fma_f32 v[60:61], v[124:125], v[60:61], v[62:63]
	v_lshlrev_b32_e32 v56, 16, v57
	v_and_b32_e32 v57, 0xffff0000, v57
	v_pk_fma_f32 v[56:57], v[108:109], v[56:57], v[60:61]
	v_lshlrev_b32_e32 v60, 16, v46
	v_and_b32_e32 v61, 0xffff0000, v46
	v_lshlrev_b32_e32 v46, 16, v47
	v_and_b32_e32 v47, 0xffff0000, v47
	v_pk_mul_f32 v[96:97], v[0:1], v[96:97] op_sel_hi:[0,1]
	v_pk_fma_f32 v[90:91], v[110:111], v[126:127], v[90:91]
	v_lshlrev_b32_e32 v110, 16, v50
	v_and_b32_e32 v111, 0xffff0000, v50
	v_lshlrev_b32_e32 v50, 16, v51
	v_and_b32_e32 v51, 0xffff0000, v51
	v_pk_fma_f32 v[60:61], v[134:135], v[60:61], v[74:75]
	v_lshlrev_b32_e32 v62, 16, v42
	v_and_b32_e32 v63, 0xffff0000, v42
	v_pk_fma_f32 v[46:47], v[136:137], v[46:47], v[76:77]
	v_lshlrev_b32_e32 v42, 16, v43
	v_and_b32_e32 v43, 0xffff0000, v43
	v_pk_fma_f32 v[50:51], v[96:97], v[50:51], v[54:55]
	v_pk_mul_f32 v[54:55], v[0:1], v[88:89] op_sel_hi:[0,1]
	v_lshlrev_b32_e32 v52, 16, v53
	v_and_b32_e32 v53, 0xffff0000, v53
	v_pk_fma_f32 v[60:61], v[118:119], v[62:63], v[60:61]
	v_lshlrev_b32_e32 v62, 16, v38
	v_and_b32_e32 v63, 0xffff0000, v38
	v_pk_fma_f32 v[42:43], v[120:121], v[42:43], v[46:47]
	v_lshlrev_b32_e32 v38, 16, v39
	v_and_b32_e32 v39, 0xffff0000, v39
	v_pk_mul_f32 v[94:95], v[0:1], v[94:95] op_sel_hi:[0,1]
	v_pk_fma_f32 v[52:53], v[54:55], v[52:53], v[56:57]
	v_pk_mul_f32 v[54:55], v[0:1], v[80:81] op_sel_hi:[0,1]
	v_pk_fma_f32 v[60:61], v[102:103], v[62:63], v[60:61]
	v_lshlrev_b32_e32 v62, 16, v34
	v_and_b32_e32 v63, 0xffff0000, v34
	v_pk_fma_f32 v[38:39], v[104:105], v[38:39], v[42:43]
	v_lshlrev_b32_e32 v34, 16, v35
	v_and_b32_e32 v35, 0xffff0000, v35
	v_lshlrev_b32_e32 v46, 16, v48
	v_and_b32_e32 v47, 0xffff0000, v48
	v_pk_fma_f32 v[90:91], v[94:95], v[110:111], v[90:91]
	v_pk_mul_f32 v[56:57], v[0:1], v[78:79] op_sel_hi:[0,1]
	v_pk_fma_f32 v[42:43], v[54:55], v[34:35], v[38:39]
	v_pk_mul_f32 v[34:35], v[0:1], v[72:73] op_sel_hi:[0,1]
	v_pk_mul_f32 v[38:39], v[0:1], v[70:71] op_sel_hi:[0,1]
	v_pk_fma_f32 v[46:47], v[130:131], v[46:47], v[66:67]
	v_lshlrev_b32_e32 v54, 16, v44
	v_and_b32_e32 v55, 0xffff0000, v44
	v_add_u32_e32 v0, 0x4800, v220
	v_pk_fma_f32 v[46:47], v[114:115], v[54:55], v[46:47]
	v_lshlrev_b32_e32 v54, 16, v40
	v_and_b32_e32 v55, 0xffff0000, v40
	ds_write2_b32 v0, v90, v91 offset1:1
	v_add_u32_e32 v0, 0x4808, v220
; DEVI unsigned cvtpk(float lo, float hi) { unsigned r; asm volatile("v_cvt_pk_bf16_f32 %0, %1, %2" : "=v"(r) : "v"(lo), "v"(hi)); return r; }
; DEVI void rnn_local_phase(const bf16_t* xr, const float* convw, const float* convb, const bf16_t* lruT, const float* ba, const float* bx, const float* lam,
;                           bf16_t* hloc, bf16_t* pcum, float* aggA, float* aggH, char* lds, int wv) {
;     ...
;             for (int i = 0; i < 16; ++i) xcf[tok * 65 + cg4 + i] = xc[i];
;             u32x4 o0 = {cvtpk(xc[0], xc[1]), cvtpk(xc[2], xc[3]), cvtpk(xc[4], xc[5]), cvtpk(xc[6], xc[7])}, o1 = {cvtpk(xc[8], xc[9]), cvtpk(xc[10], xc[11]), cvtpk(xc[12], xc[13]), cvtpk(xc[14], xc[15])};
;             *(u32x4*)(xcb + tok * 72 + cg4) = o0; *(u32x4*)(xcb + tok * 72 + cg4 + 8) = o1;
;         }
;         LBAR();
;         {
;             const bf16x8 a0 = *(const bf16x8*)(xcb + (wave * 16 + l16) * 72 + q4 * 8), a1 = *(const bf16x8*)(xcb + (wave * 16 + l16) * 72 + 32 + q4 * 8);
; #pragma unroll
;             for (int cg = 0; cg < 4; ++cg) { const int ch = cg * 16 + l16;
;                 f32x4 ca = {0.f, 0.f, 0.f, 0.f}, cx = {0.f, 0.f, 0.f, 0.f};
;                 const bf16x8 wa0 = *(const bf16x8*)(WtL + ch * 72 + q4 * 8), wa1 = *(const bf16x8*)(WtL + ch * 72 + 32 + q4 * 8);
;                 const bf16x8 wx0 = *(const bf16x8*)(WtL + (64 + ch) * 72 + q4 * 8), wx1 = *(const bf16x8*)(WtL + (64 + ch) * 72 + 32 + q4 * 8);
;                 ca = __builtin_amdgcn_mfma_f32_16x16x32_bf16(a0, wa0, ca, 0, 0, 0); ca = __builtin_amdgcn_mfma_f32_16x16x32_bf16(a1, wa1, ca, 0, 0, 0);
;                 cx = __builtin_amdgcn_mfma_f32_16x16x32_bf16(a0, wx0, cx, 0, 0, 0); cx = __builtin_amdgcn_mfma_f32_16x16x32_bf16(a1, wx1, cx, 0, 0, 0);
; #pragma unroll
;                 for (int i = 0; i < 4; ++i) { const int tk = wave * 16 + q4 * 4 + i; const float xv = xcf[tk * 65 + ch];
;                     const float r = sigmoidf_(ca[i] + bav[cg]), ig = sigmoidf_(cx[i] + bxv[cg]), la = -r * sp8[cg], a = __expf(la);
;                     const float y2 = 2.f * la; const float om = y2 < -0.05f ? 1.f - a * a : -y2 * (1.f + y2 * (0.5f + y2 * (0.16666667f + y2 * 0.041666668f)));
;                     const float u = __builtin_amdgcn_sqrtf(fmaxf(om, 0.f)) * (ig * xv);
;                     aL[tk * 65 + ch] = a; uL[tk * 65 + ch] = u; } }
	v_pk_fma_f32 v[46:47], v[98:99], v[54:55], v[46:47]
	v_lshlrev_b32_e32 v54, 16, v36
	v_and_b32_e32 v55, 0xffff0000, v36
	ds_write2_b32 v0, v50, v51 offset1:1
	v_add_u32_e32 v0, 0x4810, v220
	v_pk_fma_f32 v[46:47], v[38:39], v[54:55], v[46:47]
	v_lshlrev_b32_e32 v38, 16, v49
	v_and_b32_e32 v39, 0xffff0000, v49
	ds_write2_b32 v0, v58, v59 offset1:1
	v_add_u32_e32 v0, 0x4818, v220
	v_pk_fma_f32 v[56:57], v[56:57], v[62:63], v[60:61]
	v_pk_fma_f32 v[38:39], v[132:133], v[38:39], v[68:69]
	v_lshlrev_b32_e32 v44, 16, v45
	v_and_b32_e32 v45, 0xffff0000, v45
	ds_write2_b32 v0, v52, v53 offset1:1
	v_add_u32_e32 v0, 0x4820, v220
	v_pk_fma_f32 v[38:39], v[116:117], v[44:45], v[38:39]
	v_lshlrev_b32_e32 v40, 16, v41
	v_and_b32_e32 v41, 0xffff0000, v41
	ds_write2_b32 v0, v56, v57 offset1:1
	v_add_u32_e32 v0, 0x4828, v220
	v_pk_fma_f32 v[38:39], v[100:101], v[40:41], v[38:39]
	v_lshlrev_b32_e32 v36, 16, v37
	v_and_b32_e32 v37, 0xffff0000, v37
	ds_write2_b32 v0, v42, v43 offset1:1
	v_add_u32_e32 v0, 0x4830, v220
	v_pk_fma_f32 v[44:45], v[34:35], v[36:37], v[38:39]
	ds_write2_b32 v0, v46, v47 offset1:1
	v_add_u32_e32 v0, 0x4838, v220
	ds_write2_b32 v0, v44, v45 offset1:1
	v_cvt_pk_bf16_f32 v34, v90, v91
	v_cvt_pk_bf16_f32 v35, v50, v51
	v_cvt_pk_bf16_f32 v36, v58, v59
	v_cvt_pk_bf16_f32 v37, v52, v53
	v_cvt_pk_bf16_f32 v38, v56, v57
	v_cvt_pk_bf16_f32 v39, v42, v43
	v_cvt_pk_bf16_f32 v40, v46, v47
	v_cvt_pk_bf16_f32 v41, v44, v45
	ds_write_b128 v221, v[34:37]
	ds_write_b128 v221, v[38:41] offset:16
	s_waitcnt lgkmcnt(0)
	ds_read_b128 v[38:41], v165
	ds_read_b128 v[34:37], v165 offset:64
	ds_read_b128 v[42:45], v168
	ds_read_b128 v[46:49], v168 offset:64
	s_waitcnt lgkmcnt(0)
	v_mfma_f32_16x16x32_bf16 v[42:45], v[38:41], v[42:45], 0
	ds_read_b128 v[50:53], v168 offset:9216
	v_mfma_f32_16x16x32_bf16 v[46:49], v[34:37], v[46:49], v[42:45]
	s_nop 5
	ds_read_b128 v[42:45], v168 offset:9280
	s_waitcnt lgkmcnt(0)
	v_mfma_f32_16x16x32_bf16 v[50:53], v[38:41], v[50:53], 0
	v_add_f32_e32 v0, v149, v46
	v_mul_f32_e32 v0, 0xbfb8aa3b, v0
	v_exp_f32_e32 v0, v0
	v_mfma_f32_16x16x32_bf16 v[42:45], v[34:37], v[42:45], v[50:53]
	v_add_f32_e32 v0, 1.0, v0
	v_rcp_f32_e64 v46, -v0
	ds_read_b32 v0, v169 offset:18432
	v_mul_f32_e32 v46, v158, v46
	v_add_f32_e32 v51, v46, v46
	v_cmp_ngt_f32_e32 vcc, s40, v51
	s_and_saveexec_b64 s[10:11], vcc
	s_xor_b64 s[10:11], exec, s[10:11]
	v_mov_b32_e32 v50, 0x3e2aaaab
	v_fmamk_f32 v50, v51, 0x3d2aaaab, v50
	v_fma_f32 v50, v51, v50, 0.5
	v_fma_f32 v50, v51, v50, 1.0
	v_mul_f32_e64 v50, v50, -v51
	s_or_saveexec_b64 s[10:11], s[10:11]
	v_mul_f32_e32 v46, 0x3fb8aa3b, v46
	v_exp_f32_e32 v46, v46
	s_xor_b64 exec, exec, s[10:11]
	v_fma_f32 v50, -v46, v46, 1.0
	s_or_b64 exec, exec, s[10:11]
	v_add_f32_e32 v42, v152, v42
	v_mul_f32_e32 v42, 0xbfb8aa3b, v42
	v_exp_f32_e32 v42, v42
	v_max_f32_e32 v50, v50, v50
	v_add_f32_e32 v47, v149, v47
	v_max_f32_e32 v50, 0, v50
	v_add_f32_e32 v42, 1.0, v42
	v_rcp_f32_e32 v42, v42
	v_mul_f32_e32 v47, 0xbfb8aa3b, v47
	v_sqrt_f32_e32 v50, v50
	v_exp_f32_e32 v47, v47
	s_waitcnt lgkmcnt(0)
	v_mul_f32_e32 v0, v0, v42
	ds_write_b32 v169, v46 offset:51712
	v_mul_f32_e32 v42, v0, v50
	v_add_f32_e32 v0, 1.0, v47
	v_rcp_f32_e64 v47, -v0
	ds_read_b32 v0, v169 offset:18692
	ds_write_b32 v170, v42
	v_mul_f32_e32 v42, v158, v47
	v_add_f32_e32 v47, v42, v42
	v_cmp_ngt_f32_e32 vcc, s40, v47
	s_and_saveexec_b64 s[10:11], vcc
	s_xor_b64 s[10:11], exec, s[10:11]
	v_mov_b32_e32 v46, 0x3e2aaaab
	v_fmamk_f32 v46, v47, 0x3d2aaaab, v46
	v_fma_f32 v46, v47, v46, 0.5
	v_fma_f32 v46, v47, v46, 1.0
	v_mul_f32_e64 v46, v46, -v47
	s_or_saveexec_b64 s[10:11], s[10:11]
	v_mul_f32_e32 v42, 0x3fb8aa3b, v42
	v_exp_f32_e32 v42, v42
	s_xor_b64 exec, exec, s[10:11]
	v_fma_f32 v46, -v42, v42, 1.0
	s_or_b64 exec, exec, s[10:11]
	v_add_f32_e32 v43, v152, v43
	v_mul_f32_e32 v43, 0xbfb8aa3b, v43
	v_exp_f32_e32 v43, v43
	v_add_f32_e32 v47, v149, v48
	v_max_f32_e32 v46, v46, v46
	v_mul_f32_e32 v47, 0xbfb8aa3b, v47
	v_add_f32_e32 v43, 1.0, v43
	v_max_f32_e32 v46, 0, v46
	v_rcp_f32_e32 v43, v43
	v_exp_f32_e32 v47, v47
	v_sqrt_f32_e32 v46, v46
	ds_write_b32 v169, v42 offset:51972
	s_waitcnt lgkmcnt(0)
	v_mul_f32_e32 v0, v43, v0
	v_add_f32_e32 v42, 1.0, v47
	v_mul_f32_e32 v0, v0, v46
	v_rcp_f32_e64 v42, -v42
	ds_write_b32 v171, v0
	ds_read_b32 v0, v169 offset:18952
	v_mul_f32_e32 v42, v158, v42
	v_add_f32_e32 v46, v42, v42
	v_cmp_ngt_f32_e32 vcc, s40, v46
	s_and_saveexec_b64 s[10:11], vcc
	s_xor_b64 s[10:11], exec, s[10:11]
	v_mov_b32_e32 v43, 0x3e2aaaab
	v_fmamk_f32 v43, v46, 0x3d2aaaab, v43
	v_fma_f32 v43, v46, v43, 0.5
	v_fma_f32 v43, v46, v43, 1.0
	v_mul_f32_e64 v43, v43, -v46
	s_or_saveexec_b64 s[10:11], s[10:11]
	v_mul_f32_e32 v42, 0x3fb8aa3b, v42
	v_exp_f32_e32 v42, v42
	s_xor_b64 exec, exec, s[10:11]
	v_fma_f32 v43, -v42, v42, 1.0
	s_or_b64 exec, exec, s[10:11]
	v_add_f32_e32 v44, v152, v44
	v_mul_f32_e32 v44, 0xbfb8aa3b, v44
	v_exp_f32_e32 v44, v44
	v_add_f32_e32 v46, v149, v49
	v_max_f32_e32 v43, v43, v43
	v_mul_f32_e32 v46, 0xbfb8aa3b, v46
	v_add_f32_e32 v44, 1.0, v44
	v_max_f32_e32 v43, 0, v43
	v_rcp_f32_e32 v44, v44
	v_exp_f32_e32 v46, v46
	v_sqrt_f32_e32 v43, v43
	ds_write_b32 v169, v42 offset:52232
	s_waitcnt lgkmcnt(0)
; DEVI float sigmoidf_(float x) { return __builtin_amdgcn_rcpf(1.f + __expf(-x)); }
; DEVI void rnn_local_phase(const bf16_t* xr, const float* convw, const float* convb, const bf16_t* lruT, const float* ba, const float* bx, const float* lam,
;                           bf16_t* hloc, bf16_t* pcum, float* aggA, float* aggH, char* lds, int wv) {
;     ...
;             for (int cg = 0; cg < 4; ++cg) { const int ch = cg * 16 + l16;
;                 f32x4 ca = {0.f, 0.f, 0.f, 0.f}, cx = {0.f, 0.f, 0.f, 0.f};
;                 const bf16x8 wa0 = *(const bf16x8*)(WtL + ch * 72 + q4 * 8), wa1 = *(const bf16x8*)(WtL + ch * 72 + 32 + q4 * 8);
;                 const bf16x8 wx0 = *(const bf16x8*)(WtL + (64 + ch) * 72 + q4 * 8), wx1 = *(const bf16x8*)(WtL + (64 + ch) * 72 + 32 + q4 * 8);
;                 ca = __builtin_amdgcn_mfma_f32_16x16x32_bf16(a0, wa0, ca, 0, 0, 0); ca = __builtin_amdgcn_mfma_f32_16x16x32_bf16(a1, wa1, ca, 0, 0, 0);
;                 cx = __builtin_amdgcn_mfma_f32_16x16x32_bf16(a0, wx0, cx, 0, 0, 0); cx = __builtin_amdgcn_mfma_f32_16x16x32_bf16(a1, wx1, cx, 0, 0, 0);
; #pragma unroll
;                 for (int i = 0; i < 4; ++i) { const int tk = wave * 16 + q4 * 4 + i; const float xv = xcf[tk * 65 + ch];
;                     const float r = sigmoidf_(ca[i] + bav[cg]), ig = sigmoidf_(cx[i] + bxv[cg]), la = -r * sp8[cg], a = __expf(la);
;                     const float y2 = 2.f * la; const float om = y2 < -0.05f ? 1.f - a * a : -y2 * (1.f + y2 * (0.5f + y2 * (0.16666667f + y2 * 0.041666668f)));
;                     const float u = __builtin_amdgcn_sqrtf(fmaxf(om, 0.f)) * (ig * xv);
;                     aL[tk * 65 + ch] = a; uL[tk * 65 + ch] = u; } }
	v_mul_f32_e32 v0, v44, v0
	v_add_f32_e32 v42, 1.0, v46
	v_mul_f32_e32 v0, v0, v43
	v_rcp_f32_e64 v42, -v42
	ds_write_b32 v172, v0
	ds_read_b32 v0, v169 offset:19212
	v_mul_f32_e32 v43, v158, v42
	v_add_f32_e32 v44, v43, v43
	v_cmp_ngt_f32_e32 vcc, s40, v44
	s_and_saveexec_b64 s[10:11], vcc
	s_xor_b64 s[10:11], exec, s[10:11]
	v_mov_b32_e32 v42, 0x3e2aaaab
	v_fmamk_f32 v42, v44, 0x3d2aaaab, v42
	v_fma_f32 v42, v44, v42, 0.5
	v_fma_f32 v42, v44, v42, 1.0
	v_mul_f32_e64 v42, v42, -v44
	s_or_saveexec_b64 s[10:11], s[10:11]
	v_mul_f32_e32 v43, 0x3fb8aa3b, v43
	v_exp_f32_e32 v43, v43
	s_xor_b64 exec, exec, s[10:11]
	v_fma_f32 v42, -v43, v43, 1.0
	s_or_b64 exec, exec, s[10:11]
	v_add_f32_e32 v44, v152, v45
	v_mul_f32_e32 v44, 0xbfb8aa3b, v44
	v_exp_f32_e32 v44, v44
	v_max_f32_e32 v42, v42, v42
	v_max_f32_e32 v42, 0, v42
	v_sqrt_f32_e32 v42, v42
	v_add_f32_e32 v44, 1.0, v44
	v_rcp_f32_e32 v44, v44
	ds_write_b32 v169, v43 offset:52492
	s_waitcnt lgkmcnt(0)
	v_mul_f32_e32 v0, v44, v0
	v_mul_f32_e32 v0, v0, v42
	ds_write_b32 v173, v0
	ds_read_b128 v[42:45], v174
	ds_read_b32 v0, v169 offset:18496
	ds_read_b128 v[46:49], v174 offset:64
	ds_read_b128 v[50:53], v174 offset:9216
	s_waitcnt lgkmcnt(0)
	v_mfma_f32_16x16x32_bf16 v[42:45], v[38:41], v[42:45], 0
	v_mfma_f32_16x16x32_bf16 v[46:49], v[34:37], v[46:49], v[42:45]
	v_mfma_f32_16x16x32_bf16 v[50:53], v[38:41], v[50:53], 0
	s_nop 6
	v_add_f32_e32 v42, v150, v46
	v_mul_f32_e32 v42, 0xbfb8aa3b, v42
	v_exp_f32_e32 v46, v42
	ds_read_b128 v[42:45], v174 offset:9280
	s_waitcnt lgkmcnt(0)
	v_mfma_f32_16x16x32_bf16 v[42:45], v[34:37], v[42:45], v[50:53]
	v_add_f32_e32 v46, 1.0, v46
	v_rcp_f32_e64 v46, -v46
	s_nop 0
	v_mul_f32_e32 v46, v159, v46
	v_add_f32_e32 v51, v46, v46
	v_cmp_ngt_f32_e32 vcc, s40, v51
	s_and_saveexec_b64 s[10:11], vcc
	s_xor_b64 s[10:11], exec, s[10:11]
	v_mov_b32_e32 v50, 0x3e2aaaab
	v_fmamk_f32 v50, v51, 0x3d2aaaab, v50
	v_fma_f32 v50, v51, v50, 0.5
	v_fma_f32 v50, v51, v50, 1.0
	v_mul_f32_e64 v50, v50, -v51
	s_or_saveexec_b64 s[10:11], s[10:11]
	v_mul_f32_e32 v46, 0x3fb8aa3b, v46
	v_exp_f32_e32 v46, v46
	s_xor_b64 exec, exec, s[10:11]
	v_fma_f32 v50, -v46, v46, 1.0
	s_or_b64 exec, exec, s[10:11]
	v_add_f32_e32 v42, v153, v42
	v_mul_f32_e32 v42, 0xbfb8aa3b, v42
	v_exp_f32_e32 v42, v42
	v_max_f32_e32 v50, v50, v50
	v_add_f32_e32 v47, v150, v47
	v_max_f32_e32 v50, 0, v50
	v_add_f32_e32 v42, 1.0, v42
	v_rcp_f32_e32 v42, v42
	v_mul_f32_e32 v47, 0xbfb8aa3b, v47
	v_sqrt_f32_e32 v50, v50
	v_exp_f32_e32 v47, v47
	v_mul_f32_e32 v0, v0, v42
	ds_write_b32 v169, v46 offset:51776
	v_mul_f32_e32 v42, v0, v50
	v_add_f32_e32 v0, 1.0, v47
	v_rcp_f32_e64 v47, -v0
	ds_read_b32 v0, v176 offset:18692
	ds_write_b32 v175, v42
	v_mul_f32_e32 v42, v159, v47
	v_add_f32_e32 v47, v42, v42
	v_cmp_ngt_f32_e32 vcc, s40, v47
	s_and_saveexec_b64 s[10:11], vcc
	s_xor_b64 s[10:11], exec, s[10:11]
	v_mov_b32_e32 v46, 0x3e2aaaab
	v_fmamk_f32 v46, v47, 0x3d2aaaab, v46
	v_fma_f32 v46, v47, v46, 0.5
	v_fma_f32 v46, v47, v46, 1.0
	v_mul_f32_e64 v46, v46, -v47
	s_or_saveexec_b64 s[10:11], s[10:11]
	v_mul_f32_e32 v42, 0x3fb8aa3b, v42
	v_exp_f32_e32 v42, v42
	s_xor_b64 exec, exec, s[10:11]
	v_fma_f32 v46, -v42, v42, 1.0
	s_or_b64 exec, exec, s[10:11]
	v_add_f32_e32 v43, v153, v43
	v_mul_f32_e32 v43, 0xbfb8aa3b, v43
	v_exp_f32_e32 v43, v43
	v_add_f32_e32 v47, v150, v48
	v_max_f32_e32 v46, v46, v46
	v_mul_f32_e32 v47, 0xbfb8aa3b, v47
	v_add_f32_e32 v43, 1.0, v43
	v_max_f32_e32 v46, 0, v46
	v_rcp_f32_e32 v43, v43
	v_exp_f32_e32 v47, v47
	v_sqrt_f32_e32 v46, v46
	ds_write_b32 v176, v42 offset:51972
	s_waitcnt lgkmcnt(0)
	v_mul_f32_e32 v0, v43, v0
	v_add_f32_e32 v42, 1.0, v47
	v_mul_f32_e32 v0, v0, v46
	v_rcp_f32_e64 v42, -v42
	ds_write_b32 v177, v0
	ds_read_b32 v0, v176 offset:18952
	v_mul_f32_e32 v42, v159, v42
	v_add_f32_e32 v46, v42, v42
	v_cmp_ngt_f32_e32 vcc, s40, v46
	s_and_saveexec_b64 s[10:11], vcc
	s_xor_b64 s[10:11], exec, s[10:11]
	v_mov_b32_e32 v43, 0x3e2aaaab
	v_fmamk_f32 v43, v46, 0x3d2aaaab, v43
	v_fma_f32 v43, v46, v43, 0.5
	v_fma_f32 v43, v46, v43, 1.0
	v_mul_f32_e64 v43, v43, -v46
	s_or_saveexec_b64 s[10:11], s[10:11]
	v_mul_f32_e32 v42, 0x3fb8aa3b, v42
	v_exp_f32_e32 v42, v42
	s_xor_b64 exec, exec, s[10:11]
	v_fma_f32 v43, -v42, v42, 1.0
	s_or_b64 exec, exec, s[10:11]
	v_add_f32_e32 v44, v153, v44
	v_mul_f32_e32 v44, 0xbfb8aa3b, v44
	v_exp_f32_e32 v44, v44
	v_add_f32_e32 v46, v150, v49
	v_max_f32_e32 v43, v43, v43
	v_mul_f32_e32 v46, 0xbfb8aa3b, v46
	v_add_f32_e32 v44, 1.0, v44
	v_max_f32_e32 v43, 0, v43
	v_rcp_f32_e32 v44, v44
	v_exp_f32_e32 v46, v46
	v_sqrt_f32_e32 v43, v43
	ds_write_b32 v176, v42 offset:52232
	s_waitcnt lgkmcnt(0)
	v_mul_f32_e32 v0, v44, v0
	v_add_f32_e32 v42, 1.0, v46
	v_mul_f32_e32 v0, v0, v43
	v_rcp_f32_e64 v42, -v42
	ds_write_b32 v178, v0
	ds_read_b32 v0, v176 offset:19212
	v_mul_f32_e32 v43, v159, v42
	v_add_f32_e32 v44, v43, v43
	v_cmp_ngt_f32_e32 vcc, s40, v44
	s_and_saveexec_b64 s[10:11], vcc
	s_xor_b64 s[10:11], exec, s[10:11]
	v_mov_b32_e32 v42, 0x3e2aaaab
	v_fmamk_f32 v42, v44, 0x3d2aaaab, v42
	v_fma_f32 v42, v44, v42, 0.5
	v_fma_f32 v42, v44, v42, 1.0
	v_mul_f32_e64 v42, v42, -v44
	s_or_saveexec_b64 s[10:11], s[10:11]
	v_mul_f32_e32 v43, 0x3fb8aa3b, v43
	v_exp_f32_e32 v43, v43
	s_xor_b64 exec, exec, s[10:11]
	v_fma_f32 v42, -v43, v43, 1.0
	s_or_b64 exec, exec, s[10:11]
	v_add_f32_e32 v44, v153, v45
	v_mul_f32_e32 v44, 0xbfb8aa3b, v44
	v_exp_f32_e32 v44, v44
	v_max_f32_e32 v42, v42, v42
	v_max_f32_e32 v42, 0, v42
	v_sqrt_f32_e32 v42, v42
	v_add_f32_e32 v44, 1.0, v44
	v_rcp_f32_e32 v44, v44
	ds_write_b32 v176, v43 offset:52492
	s_waitcnt lgkmcnt(0)
; DEVI float sigmoidf_(float x) { return __builtin_amdgcn_rcpf(1.f + __expf(-x)); }
; DEVI void rnn_local_phase(const bf16_t* xr, const float* convw, const float* convb, const bf16_t* lruT, const float* ba, const float* bx, const float* lam,
;                           bf16_t* hloc, bf16_t* pcum, float* aggA, float* aggH, char* lds, int wv) {
;     ...
;             for (int cg = 0; cg < 4; ++cg) { const int ch = cg * 16 + l16;
;                 f32x4 ca = {0.f, 0.f, 0.f, 0.f}, cx = {0.f, 0.f, 0.f, 0.f};
;                 const bf16x8 wa0 = *(const bf16x8*)(WtL + ch * 72 + q4 * 8), wa1 = *(const bf16x8*)(WtL + ch * 72 + 32 + q4 * 8);
;                 const bf16x8 wx0 = *(const bf16x8*)(WtL + (64 + ch) * 72 + q4 * 8), wx1 = *(const bf16x8*)(WtL + (64 + ch) * 72 + 32 + q4 * 8);
;                 ca = __builtin_amdgcn_mfma_f32_16x16x32_bf16(a0, wa0, ca, 0, 0, 0); ca = __builtin_amdgcn_mfma_f32_16x16x32_bf16(a1, wa1, ca, 0, 0, 0);
;                 cx = __builtin_amdgcn_mfma_f32_16x16x32_bf16(a0, wx0, cx, 0, 0, 0); cx = __builtin_amdgcn_mfma_f32_16x16x32_bf16(a1, wx1, cx, 0, 0, 0);
; #pragma unroll
;                 for (int i = 0; i < 4; ++i) { const int tk = wave * 16 + q4 * 4 + i; const float xv = xcf[tk * 65 + ch];
;                     const float r = sigmoidf_(ca[i] + bav[cg]), ig = sigmoidf_(cx[i] + bxv[cg]), la = -r * sp8[cg], a = __expf(la);
;                     const float y2 = 2.f * la; const float om = y2 < -0.05f ? 1.f - a * a : -y2 * (1.f + y2 * (0.5f + y2 * (0.16666667f + y2 * 0.041666668f)));
;                     const float u = __builtin_amdgcn_sqrtf(fmaxf(om, 0.f)) * (ig * xv);
;                     aL[tk * 65 + ch] = a; uL[tk * 65 + ch] = u; } }
	v_mul_f32_e32 v0, v44, v0
	v_mul_f32_e32 v0, v0, v42
	ds_write_b32 v179, v0
	ds_read_b128 v[42:45], v180
	ds_read_b32 v0, v169 offset:18560
	ds_read_b128 v[46:49], v180 offset:64
	ds_read_b128 v[50:53], v180 offset:9216
	s_waitcnt lgkmcnt(0)
	v_mfma_f32_16x16x32_bf16 v[42:45], v[38:41], v[42:45], 0
	v_mfma_f32_16x16x32_bf16 v[46:49], v[34:37], v[46:49], v[42:45]
	v_mfma_f32_16x16x32_bf16 v[50:53], v[38:41], v[50:53], 0
	s_nop 6
	v_add_f32_e32 v42, v151, v46
	v_mul_f32_e32 v42, 0xbfb8aa3b, v42
	v_exp_f32_e32 v46, v42
	ds_read_b128 v[42:45], v180 offset:9280
	s_waitcnt lgkmcnt(0)
	v_mfma_f32_16x16x32_bf16 v[42:45], v[34:37], v[42:45], v[50:53]
	v_add_f32_e32 v46, 1.0, v46
	v_rcp_f32_e64 v46, -v46
	s_nop 0
	v_mul_f32_e32 v46, v160, v46
	v_add_f32_e32 v51, v46, v46
	v_cmp_ngt_f32_e32 vcc, s40, v51
	s_and_saveexec_b64 s[10:11], vcc
	s_xor_b64 s[10:11], exec, s[10:11]
	v_mov_b32_e32 v50, 0x3e2aaaab
	v_fmamk_f32 v50, v51, 0x3d2aaaab, v50
	v_fma_f32 v50, v51, v50, 0.5
	v_fma_f32 v50, v51, v50, 1.0
	v_mul_f32_e64 v50, v50, -v51
	s_or_saveexec_b64 s[10:11], s[10:11]
	v_mul_f32_e32 v46, 0x3fb8aa3b, v46
	v_exp_f32_e32 v46, v46
	s_xor_b64 exec, exec, s[10:11]
	v_fma_f32 v50, -v46, v46, 1.0
	s_or_b64 exec, exec, s[10:11]
	v_add_f32_e32 v42, v154, v42
	v_mul_f32_e32 v42, 0xbfb8aa3b, v42
	v_exp_f32_e32 v42, v42
	v_max_f32_e32 v50, v50, v50
	v_add_f32_e32 v47, v151, v47
	v_max_f32_e32 v50, 0, v50
	v_add_f32_e32 v42, 1.0, v42
	v_rcp_f32_e32 v42, v42
	v_mul_f32_e32 v47, 0xbfb8aa3b, v47
	v_sqrt_f32_e32 v50, v50
	v_exp_f32_e32 v47, v47
	v_mul_f32_e32 v0, v0, v42
	ds_write_b32 v169, v46 offset:51840
	v_mul_f32_e32 v42, v0, v50
	v_add_f32_e32 v0, 1.0, v47
	v_rcp_f32_e64 v47, -v0
	ds_read_b32 v0, v182 offset:18692
	ds_write_b32 v181, v42
	v_mul_f32_e32 v42, v160, v47
	v_add_f32_e32 v47, v42, v42
	v_cmp_ngt_f32_e32 vcc, s40, v47
	s_and_saveexec_b64 s[10:11], vcc
	s_xor_b64 s[10:11], exec, s[10:11]
	v_mov_b32_e32 v46, 0x3e2aaaab
	v_fmamk_f32 v46, v47, 0x3d2aaaab, v46
	v_fma_f32 v46, v47, v46, 0.5
	v_fma_f32 v46, v47, v46, 1.0
	v_mul_f32_e64 v46, v46, -v47
	s_or_saveexec_b64 s[10:11], s[10:11]
	v_mul_f32_e32 v42, 0x3fb8aa3b, v42
	v_exp_f32_e32 v42, v42
	s_xor_b64 exec, exec, s[10:11]
	v_fma_f32 v46, -v42, v42, 1.0
	s_or_b64 exec, exec, s[10:11]
	v_add_f32_e32 v43, v154, v43
	v_mul_f32_e32 v43, 0xbfb8aa3b, v43
	v_exp_f32_e32 v43, v43
	v_add_f32_e32 v47, v151, v48
	v_max_f32_e32 v46, v46, v46
	v_mul_f32_e32 v47, 0xbfb8aa3b, v47
	v_add_f32_e32 v43, 1.0, v43
	v_max_f32_e32 v46, 0, v46
	v_rcp_f32_e32 v43, v43
	v_exp_f32_e32 v47, v47
	v_sqrt_f32_e32 v46, v46
	ds_write_b32 v182, v42 offset:51972
	s_waitcnt lgkmcnt(0)
	v_mul_f32_e32 v0, v43, v0
	v_add_f32_e32 v42, 1.0, v47
	v_mul_f32_e32 v0, v0, v46
	v_rcp_f32_e64 v42, -v42
	ds_write_b32 v183, v0
	ds_read_b32 v0, v182 offset:18952
	v_mul_f32_e32 v42, v160, v42
	v_add_f32_e32 v46, v42, v42
	v_cmp_ngt_f32_e32 vcc, s40, v46
	s_and_saveexec_b64 s[10:11], vcc
	s_xor_b64 s[10:11], exec, s[10:11]
	v_mov_b32_e32 v43, 0x3e2aaaab
	v_fmamk_f32 v43, v46, 0x3d2aaaab, v43
	v_fma_f32 v43, v46, v43, 0.5
	v_fma_f32 v43, v46, v43, 1.0
	v_mul_f32_e64 v43, v43, -v46
	s_or_saveexec_b64 s[10:11], s[10:11]
	v_mul_f32_e32 v42, 0x3fb8aa3b, v42
	v_exp_f32_e32 v42, v42
	s_xor_b64 exec, exec, s[10:11]
	v_fma_f32 v43, -v42, v42, 1.0
	s_or_b64 exec, exec, s[10:11]
	v_add_f32_e32 v44, v154, v44
	v_mul_f32_e32 v44, 0xbfb8aa3b, v44
	v_exp_f32_e32 v44, v44
	v_add_f32_e32 v46, v151, v49
	v_max_f32_e32 v43, v43, v43
	v_mul_f32_e32 v46, 0xbfb8aa3b, v46
	v_add_f32_e32 v44, 1.0, v44
	v_max_f32_e32 v43, 0, v43
	v_rcp_f32_e32 v44, v44
	v_exp_f32_e32 v46, v46
	v_sqrt_f32_e32 v43, v43
	ds_write_b32 v182, v42 offset:52232
	s_waitcnt lgkmcnt(0)
	v_mul_f32_e32 v0, v44, v0
	v_add_f32_e32 v42, 1.0, v46
	v_mul_f32_e32 v0, v0, v43
	v_rcp_f32_e64 v42, -v42
	ds_write_b32 v184, v0
	ds_read_b32 v0, v182 offset:19212
	v_mul_f32_e32 v43, v160, v42
	v_add_f32_e32 v44, v43, v43
	v_cmp_ngt_f32_e32 vcc, s40, v44
	s_and_saveexec_b64 s[10:11], vcc
	s_xor_b64 s[10:11], exec, s[10:11]
	v_mov_b32_e32 v42, 0x3e2aaaab
	v_fmamk_f32 v42, v44, 0x3d2aaaab, v42
	v_fma_f32 v42, v44, v42, 0.5
	v_fma_f32 v42, v44, v42, 1.0
	v_mul_f32_e64 v42, v42, -v44
	s_or_saveexec_b64 s[10:11], s[10:11]
	v_mul_f32_e32 v43, 0x3fb8aa3b, v43
	v_exp_f32_e32 v43, v43
	s_xor_b64 exec, exec, s[10:11]
	v_fma_f32 v42, -v43, v43, 1.0
	s_or_b64 exec, exec, s[10:11]
	v_add_f32_e32 v44, v154, v45
	v_mul_f32_e32 v44, 0xbfb8aa3b, v44
	v_exp_f32_e32 v44, v44
	v_max_f32_e32 v42, v42, v42
	v_max_f32_e32 v42, 0, v42
	v_sqrt_f32_e32 v42, v42
	v_add_f32_e32 v44, 1.0, v44
	v_rcp_f32_e32 v44, v44
	ds_write_b32 v182, v43 offset:52492
	s_waitcnt lgkmcnt(0)
	v_mul_f32_e32 v0, v44, v0
	v_mul_f32_e32 v0, v0, v42
	ds_write_b32 v185, v0
	ds_read_b128 v[42:45], v186
	ds_read_b128 v[46:49], v186 offset:64
	ds_read_b128 v[50:53], v186 offset:9216
	s_waitcnt lgkmcnt(0)
	v_mfma_f32_16x16x32_bf16 v[42:45], v[38:41], v[42:45], 0
	v_mfma_f32_16x16x32_bf16 v[42:45], v[34:37], v[46:49], v[42:45]
	ds_read_b128 v[46:49], v186 offset:9280
	v_mfma_f32_16x16x32_bf16 v[38:41], v[38:41], v[50:53], 0
	s_nop 5
	v_add_f32_e32 v0, v156, v42
	v_mul_f32_e32 v0, 0xbfb8aa3b, v0
	v_exp_f32_e32 v0, v0
	s_nop 0
	v_add_f32_e32 v0, 1.0, v0
	v_rcp_f32_e64 v42, -v0
	ds_read_b32 v0, v169 offset:18624
	s_waitcnt lgkmcnt(0)
; DEVI float sigmoidf_(float x) { return __builtin_amdgcn_rcpf(1.f + __expf(-x)); }
; #define LBAR() do { asm volatile("s_waitcnt lgkmcnt(0)" ::: "memory"); __builtin_amdgcn_s_barrier(); asm volatile("" ::: "memory"); } while (0)
; DEVI void rnn_local_phase(const bf16_t* xr, const float* convw, const float* convb, const bf16_t* lruT, const float* ba, const float* bx, const float* lam,
;                           bf16_t* hloc, bf16_t* pcum, float* aggA, float* aggH, char* lds, int wv) {
;     ...
;             for (int cg = 0; cg < 4; ++cg) { const int ch = cg * 16 + l16;
;                 f32x4 ca = {0.f, 0.f, 0.f, 0.f}, cx = {0.f, 0.f, 0.f, 0.f};
;                 const bf16x8 wa0 = *(const bf16x8*)(WtL + ch * 72 + q4 * 8), wa1 = *(const bf16x8*)(WtL + ch * 72 + 32 + q4 * 8);
;                 const bf16x8 wx0 = *(const bf16x8*)(WtL + (64 + ch) * 72 + q4 * 8), wx1 = *(const bf16x8*)(WtL + (64 + ch) * 72 + 32 + q4 * 8);
;                 ca = __builtin_amdgcn_mfma_f32_16x16x32_bf16(a0, wa0, ca, 0, 0, 0); ca = __builtin_amdgcn_mfma_f32_16x16x32_bf16(a1, wa1, ca, 0, 0, 0);
;                 cx = __builtin_amdgcn_mfma_f32_16x16x32_bf16(a0, wx0, cx, 0, 0, 0); cx = __builtin_amdgcn_mfma_f32_16x16x32_bf16(a1, wx1, cx, 0, 0, 0);
; #pragma unroll
;                 for (int i = 0; i < 4; ++i) { const int tk = wave * 16 + q4 * 4 + i; const float xv = xcf[tk * 65 + ch];
;                     const float r = sigmoidf_(ca[i] + bav[cg]), ig = sigmoidf_(cx[i] + bxv[cg]), la = -r * sp8[cg], a = __expf(la);
;                     const float y2 = 2.f * la; const float om = y2 < -0.05f ? 1.f - a * a : -y2 * (1.f + y2 * (0.5f + y2 * (0.16666667f + y2 * 0.041666668f)));
;                     const float u = __builtin_amdgcn_sqrtf(fmaxf(om, 0.f)) * (ig * xv);
;                     aL[tk * 65 + ch] = a; uL[tk * 65 + ch] = u; } }
;         }
;         LBAR();
;         {
;             float h = 0.f, P = 1.f;
	v_mfma_f32_16x16x32_bf16 v[34:37], v[34:37], v[46:49], v[38:41]
	s_nop 2
	v_mul_f32_e32 v38, v161, v42
	v_add_f32_e32 v40, v38, v38
	v_cmp_ngt_f32_e32 vcc, s40, v40
	s_and_saveexec_b64 s[10:11], vcc
	s_xor_b64 s[10:11], exec, s[10:11]
	v_mov_b32_e32 v39, 0x3e2aaaab
	v_fmamk_f32 v39, v40, 0x3d2aaaab, v39
	v_fma_f32 v39, v40, v39, 0.5
	v_fma_f32 v39, v40, v39, 1.0
	v_mul_f32_e64 v39, v39, -v40
	s_or_saveexec_b64 s[10:11], s[10:11]
	v_mul_f32_e32 v38, 0x3fb8aa3b, v38
	v_exp_f32_e32 v38, v38
	s_xor_b64 exec, exec, s[10:11]
	v_fma_f32 v39, -v38, v38, 1.0
	s_or_b64 exec, exec, s[10:11]
	v_add_f32_e32 v34, v155, v34
	v_mul_f32_e32 v34, 0xbfb8aa3b, v34
	v_exp_f32_e32 v34, v34
	v_max_f32_e32 v39, v39, v39
	v_add_f32_e32 v40, v156, v43
	v_max_f32_e32 v39, 0, v39
	v_add_f32_e32 v34, 1.0, v34
	v_rcp_f32_e32 v34, v34
	v_mul_f32_e32 v40, 0xbfb8aa3b, v40
	v_sqrt_f32_e32 v39, v39
	v_exp_f32_e32 v40, v40
	v_mul_f32_e32 v0, v0, v34
	ds_write_b32 v169, v38 offset:51904
	v_mul_f32_e32 v34, v0, v39
	v_add_f32_e32 v0, 1.0, v40
	v_rcp_f32_e64 v39, -v0
	ds_read_b32 v0, v188 offset:18692
	ds_write_b32 v187, v34
	v_mul_f32_e32 v34, v161, v39
	v_add_f32_e32 v39, v34, v34
	v_cmp_ngt_f32_e32 vcc, s40, v39
	s_and_saveexec_b64 s[10:11], vcc
	s_xor_b64 s[10:11], exec, s[10:11]
	v_mov_b32_e32 v38, 0x3e2aaaab
	v_fmamk_f32 v38, v39, 0x3d2aaaab, v38
	v_fma_f32 v38, v39, v38, 0.5
	v_fma_f32 v38, v39, v38, 1.0
	v_mul_f32_e64 v38, v38, -v39
	s_or_saveexec_b64 s[10:11], s[10:11]
	v_mul_f32_e32 v34, 0x3fb8aa3b, v34
	v_exp_f32_e32 v34, v34
	s_xor_b64 exec, exec, s[10:11]
	v_fma_f32 v38, -v34, v34, 1.0
	s_or_b64 exec, exec, s[10:11]
	v_add_f32_e32 v35, v155, v35
	v_mul_f32_e32 v35, 0xbfb8aa3b, v35
	v_exp_f32_e32 v35, v35
	v_add_f32_e32 v39, v156, v44
	v_max_f32_e32 v38, v38, v38
	v_mul_f32_e32 v39, 0xbfb8aa3b, v39
	v_add_f32_e32 v35, 1.0, v35
	v_max_f32_e32 v38, 0, v38
	v_rcp_f32_e32 v35, v35
	v_exp_f32_e32 v39, v39
	v_sqrt_f32_e32 v38, v38
	ds_write_b32 v188, v34 offset:51972
	s_waitcnt lgkmcnt(0)
	v_mul_f32_e32 v0, v35, v0
	v_add_f32_e32 v34, 1.0, v39
	v_mul_f32_e32 v0, v0, v38
	v_rcp_f32_e64 v34, -v34
	ds_write_b32 v189, v0
	ds_read_b32 v0, v188 offset:18952
	v_mul_f32_e32 v34, v161, v34
	v_add_f32_e32 v38, v34, v34
	v_cmp_ngt_f32_e32 vcc, s40, v38
	s_and_saveexec_b64 s[10:11], vcc
	s_xor_b64 s[10:11], exec, s[10:11]
	v_mov_b32_e32 v35, 0x3e2aaaab
	v_fmamk_f32 v35, v38, 0x3d2aaaab, v35
	v_fma_f32 v35, v38, v35, 0.5
	v_fma_f32 v35, v38, v35, 1.0
	v_mul_f32_e64 v35, v35, -v38
	s_or_saveexec_b64 s[10:11], s[10:11]
	v_mul_f32_e32 v34, 0x3fb8aa3b, v34
	v_exp_f32_e32 v34, v34
	s_xor_b64 exec, exec, s[10:11]
	v_fma_f32 v35, -v34, v34, 1.0
	s_or_b64 exec, exec, s[10:11]
	v_add_f32_e32 v36, v155, v36
	v_mul_f32_e32 v36, 0xbfb8aa3b, v36
	v_exp_f32_e32 v36, v36
	v_add_f32_e32 v38, v156, v45
	v_max_f32_e32 v35, v35, v35
	v_mul_f32_e32 v38, 0xbfb8aa3b, v38
	v_add_f32_e32 v36, 1.0, v36
	v_max_f32_e32 v35, 0, v35
	v_rcp_f32_e32 v36, v36
	v_exp_f32_e32 v38, v38
	v_sqrt_f32_e32 v35, v35
	ds_write_b32 v188, v34 offset:52232
	s_waitcnt lgkmcnt(0)
	v_mul_f32_e32 v0, v36, v0
	v_add_f32_e32 v34, 1.0, v38
	v_mul_f32_e32 v0, v0, v35
	v_rcp_f32_e64 v35, -v34
	ds_write_b32 v190, v0
	ds_read_b32 v34, v188 offset:19212
	v_mul_f32_e32 v0, v161, v35
	v_add_f32_e32 v35, v0, v0
	v_cmp_ngt_f32_e32 vcc, s40, v35
	s_and_saveexec_b64 s[10:11], vcc
	s_xor_b64 s[10:11], exec, s[10:11]
	v_mov_b32_e32 v36, 0x3e2aaaab
	v_fmamk_f32 v36, v35, 0x3d2aaaab, v36
	v_fma_f32 v36, v35, v36, 0.5
	v_fma_f32 v36, v35, v36, 1.0
	v_mul_f32_e64 v36, v36, -v35
	s_or_saveexec_b64 s[10:11], s[10:11]
	v_mul_f32_e32 v0, 0x3fb8aa3b, v0
	v_exp_f32_e32 v35, v0
	s_xor_b64 exec, exec, s[10:11]
	v_fma_f32 v36, -v35, v35, 1.0
	s_or_b64 exec, exec, s[10:11]
	v_add_f32_e32 v0, v155, v37
	v_mul_f32_e32 v0, 0xbfb8aa3b, v0
	v_exp_f32_e32 v37, v0
	v_max_f32_e32 v38, v36, v36
	v_max_f32_e32 v38, 0, v38
	v_sqrt_f32_e32 v38, v38
	v_add_f32_e32 v37, 1.0, v37
	v_rcp_f32_e32 v37, v37
	v_add_u32_e32 v39, 0xcc00, v192
	v_mov_b32_e32 v0, 1.0
	v_mov_b32_e32 v36, 0
	s_waitcnt lgkmcnt(0)
	v_mul_f32_e32 v34, v37, v34
	v_mul_f32_e32 v34, v34, v38
	ds_write_b32 v188, v35 offset:52492
	ds_write_b32 v191, v34
	s_waitcnt lgkmcnt(0)
	s_barrier
; #define LBAR() do { asm volatile("s_waitcnt lgkmcnt(0)" ::: "memory"); __builtin_amdgcn_s_barrier(); asm volatile("" ::: "memory"); } while (0)
; DEVI void rnn_local_phase(const bf16_t* xr, const float* convw, const float* convb, const bf16_t* lruT, const float* ba, const float* bx, const float* lam,
;                           bf16_t* hloc, bf16_t* pcum, float* aggA, float* aggH, char* lds, int wv) {
;     ...
;             float h = 0.f, P = 1.f;
; #pragma unroll
;             for (int i = 0; i < 16; ++i) { const int o = (wave * 16 + i) * 65 + lane; const float a = aL[o], u = uL[o]; h = a * h + u; P *= a; uL[o] = h; aL[o] = P; }
;             segA[wave * 64 + lane] = P; segH[wave * 64 + lane] = h;
;         }
;         LBAR();
;         {
;             float Ain = 1.f, Hin = 0.f;
;             for (int s = 0; s < wave; ++s) { const float As = segA[s * 64 + lane], Hs = segH[s * 64 + lane]; Hin = As * Hin + Hs; Ain *= As; }
	v_add_u32_e32 v215, 0x14c00, v192
	ds_read_b32 v212, v192 offset:51712
	ds_read_b32 v213, v215
	ds_read_b32 v222, v192 offset:51972
	ds_read_b32 v223, v215 offset:260
	ds_read_b32 v224, v192 offset:52232
	ds_read_b32 v225, v215 offset:520
	ds_read_b32 v226, v192 offset:52492
	ds_read_b32 v227, v215 offset:780
	ds_read_b32 v228, v192 offset:52752
	ds_read_b32 v229, v215 offset:1040
	ds_read_b32 v230, v192 offset:53012
	ds_read_b32 v231, v215 offset:1300
	ds_read_b32 v232, v192 offset:53272
	ds_read_b32 v233, v215 offset:1560
	ds_read_b32 v234, v192 offset:53532
	ds_read_b32 v235, v215 offset:1820
	ds_read_b32 v236, v192 offset:53792
	ds_read_b32 v237, v215 offset:2080
	ds_read_b32 v238, v192 offset:54052
	ds_read_b32 v239, v215 offset:2340
	ds_read_b32 v240, v192 offset:54312
	ds_read_b32 v241, v215 offset:2600
	ds_read_b32 v242, v192 offset:54572
	ds_read_b32 v243, v215 offset:2860
	ds_read_b32 v244, v192 offset:54832
	ds_read_b32 v245, v215 offset:3120
	ds_read_b32 v246, v192 offset:55092
	ds_read_b32 v247, v215 offset:3380
	ds_read_b32 v248, v192 offset:55352
	ds_read_b32 v249, v215 offset:3640
	ds_read_b32 v250, v192 offset:55612
	ds_read_b32 v251, v215 offset:3900
	s_andn2_b64 vcc, exec, s[4:5]
	s_waitcnt lgkmcnt(15)
	v_fmac_f32_e32 v213, 0, v212
	v_fmac_f32_e32 v223, v213, v222
	v_mul_f32_e32 v222, v212, v222
	v_fmac_f32_e32 v225, v223, v224
	v_mul_f32_e32 v224, v222, v224
	v_fmac_f32_e32 v227, v225, v226
	v_mul_f32_e32 v226, v224, v226
	v_fmac_f32_e32 v229, v227, v228
	v_mul_f32_e32 v228, v226, v228
	v_fmac_f32_e32 v231, v229, v230
	v_mul_f32_e32 v230, v228, v230
	v_fmac_f32_e32 v233, v231, v232
	v_mul_f32_e32 v232, v230, v232
	v_fmac_f32_e32 v235, v233, v234
	v_mul_f32_e32 v234, v232, v234
	s_waitcnt lgkmcnt(14)
	v_fmac_f32_e32 v237, v235, v236
	v_mul_f32_e32 v236, v234, v236
	s_waitcnt lgkmcnt(12)
	v_fmac_f32_e32 v239, v237, v238
	v_mul_f32_e32 v238, v236, v238
	s_waitcnt lgkmcnt(10)
	v_fmac_f32_e32 v241, v239, v240
	v_mul_f32_e32 v240, v238, v240
	s_waitcnt lgkmcnt(8)
	v_fmac_f32_e32 v243, v241, v242
	v_mul_f32_e32 v242, v240, v242
	s_waitcnt lgkmcnt(6)
	v_fmac_f32_e32 v245, v243, v244
	v_mul_f32_e32 v244, v242, v244
	s_waitcnt lgkmcnt(4)
	v_fmac_f32_e32 v247, v245, v246
	v_mul_f32_e32 v246, v244, v246
	s_waitcnt lgkmcnt(2)
	v_fmac_f32_e32 v249, v247, v248
	v_mul_f32_e32 v248, v246, v248
	s_waitcnt lgkmcnt(0)
	v_fmac_f32_e32 v251, v249, v250
	v_mul_f32_e32 v250, v248, v250
	ds_write_b32 v166, v250
	ds_write_b32 v167, v251
	s_waitcnt lgkmcnt(0)
	s_barrier
	s_cbranch_vccnz .LBB0_190
	v_mov_b32_e32 v0, 1.0
	v_mov_b32_e32 v36, 0
	v_add_u32_e32 v215, 0xfffff800, v219
	ds_read_b32 v34, v215
	ds_read_b32 v35, v219
	ds_read_b32 v37, v215 offset:256
	ds_read_b32 v38, v219 offset:256
	ds_read_b32 v39, v215 offset:512
	ds_read_b32 v40, v219 offset:512
	ds_read_b32 v41, v215 offset:768
	ds_read_b32 v42, v219 offset:768
	ds_read_b32 v43, v215 offset:1024
	ds_read_b32 v44, v219 offset:1024
	ds_read_b32 v45, v215 offset:1280
	ds_read_b32 v198, v219 offset:1280
	ds_read_b32 v199, v215 offset:1536
	ds_read_b32 v214, v219 offset:1536
	s_waitcnt lgkmcnt(12)
	v_mul_f32_e32 v0, v0, v34
	v_fmac_f32_e32 v35, v36, v34
	v_mov_b32_e32 v36, v35
	s_cmp_le_u32 s46, 1
	s_cbranch_scc1 .Lmy_rnn_cdone
	s_waitcnt lgkmcnt(10)
	v_mul_f32_e32 v0, v0, v37
	v_fmac_f32_e32 v38, v36, v37
	v_mov_b32_e32 v36, v38
	s_cmp_le_u32 s46, 2
	s_cbranch_scc1 .Lmy_rnn_cdone
	s_waitcnt lgkmcnt(8)
	v_mul_f32_e32 v0, v0, v39
	v_fmac_f32_e32 v40, v36, v39
	v_mov_b32_e32 v36, v40
	s_cmp_le_u32 s46, 3
	s_cbranch_scc1 .Lmy_rnn_cdone
	s_waitcnt lgkmcnt(6)
	v_mul_f32_e32 v0, v0, v41
	v_fmac_f32_e32 v42, v36, v41
	v_mov_b32_e32 v36, v42
	s_cmp_le_u32 s46, 4
	s_cbranch_scc1 .Lmy_rnn_cdone
	s_waitcnt lgkmcnt(4)
	v_mul_f32_e32 v0, v0, v43
	v_fmac_f32_e32 v44, v36, v43
	v_mov_b32_e32 v36, v44
	s_cmp_le_u32 s46, 5
	s_cbranch_scc1 .Lmy_rnn_cdone
	s_waitcnt lgkmcnt(2)
	v_mul_f32_e32 v0, v0, v45
	v_fmac_f32_e32 v198, v36, v45
	v_mov_b32_e32 v36, v198
	s_cmp_le_u32 s46, 6
	s_cbranch_scc1 .Lmy_rnn_cdone
	s_waitcnt lgkmcnt(0)
	v_mul_f32_e32 v0, v0, v199
	v_fmac_f32_e32 v214, v36, v199
	v_mov_b32_e32 v36, v214

; DEVI unsigned cvtpk(float lo, float hi) { unsigned r; asm volatile("v_cvt_pk_bf16_f32 %0, %1, %2" : "=v"(r) : "v"(lo), "v"(hi)); return r; }
; template <int CTRL> DEVI float dpp(float x) { return __builtin_bit_cast(float, __builtin_amdgcn_mov_dpp(__builtin_bit_cast(int, x), CTRL, 0xf, 0xf, true)); }
; #define SBAR() __builtin_amdgcn_sched_barrier(0)
; DEVI int crow(int r, int hi) { return (r & 3) + 8 * (r >> 2) + 4 * hi; }
; #define SEAM_K0() do { VMWN(NQL); SWRITE_HK(0); SBAR(); } while (0)
; DEVI void block(const BlockRef& cur, const BlockRef& nxt, char* lds, Seam& S, int wv) {
;     ...
;     SBAR(); SEAM_K0();
;     if (hi == 0) li_l[r32] = l_reg; asm volatile("s_waitcnt lgkmcnt(0)" ::: "memory");
;     float rli[16];
; #pragma unroll
;     for (int r = 0; r < 16; ++r) rli[r] = __builtin_amdgcn_rcpf(li_l[crow(r, hi)]);
;     bf16_t* Ow = cur.O + (size_t)(wid * QBLK) * RS;
; #pragma unroll
;     for (int r = 0; r < 16; ++r) { const int orow = crow(r, hi);
; #pragma unroll
;         for (int d0 = 0; d0 < 4; ++d0) { const float v = o[d0][r] * rli[r];
;             const float vn = dpp<0xB1>(v);
;             if ((r32 & 1) == 0) *(unsigned*)(Ow + (size_t)orow * RS + d0 * 32 + r32) = cvtpk(v, vn); } }
.LBB0_247:
	s_or_b64 exec, exec, s[6:7]
	s_waitcnt vmcnt(8)
	s_waitcnt vmcnt(0) lgkmcnt(0)
	ds_write_b128 v224, v[120:123] offset:32768
	ds_write_b128 v224, v[124:127] offset:40960
	v_cmp_gt_u32_e32 vcc, 32, v220
	s_mov_b64 s[4:5], exec
	s_and_b64 s[6:7], s[4:5], vcc
	v_mov_b32_e32 v1, v215
	s_mov_b64 exec, s[6:7]
	ds_write_b32 v226, v2
	s_or_b64 exec, exec, s[4:5]
	s_waitcnt lgkmcnt(0)
	ds_read_b128 v[80:83], v225
	s_ashr_i32 s89, s88, 31
	ds_read_b128 v[10:13], v225 offset:32
	ds_read_b128 v[6:9], v225 offset:64
	ds_read_b128 v[2:5], v225 offset:96
	s_lshl_b64 s[4:5], s[88:89], 11
	s_add_u32 s6, s86, s4
	s_waitcnt lgkmcnt(3)
	v_rcp_f32_e32 v80, v80
	v_and_b32_e32 v0, 1, v219
	s_addc_u32 s7, s87, s5
	v_cmp_eq_u32_e64 s[4:5], 0, v0
	v_lshlrev_b32_e32 v0, 1, v222
	v_lshl_add_u64 v[14:15], s[6:7], 0, v[0:1]
	v_lshlrev_b32_e32 v0, 13, v221
	v_lshl_add_u64 v[14:15], v[14:15], 0, v[0:1]
	v_mul_f32_e32 v0, v64, v80
	s_nop 1
	v_mov_b32_dpp v64, v0 quad_perm:[1,0,3,2] row_mask:0xf bank_mask:0xf bound_ctrl:1
	s_and_saveexec_b64 s[6:7], s[4:5]
	s_cbranch_execz .LBB0_251
	v_cvt_pk_bf16_f32 v0, v0, v64
	flat_store_dword v[14:15], v0 nt
.LBB0_251:
	s_or_b64 exec, exec, s[6:7]
	v_mul_f32_e32 v0, v48, v80
	s_nop 1
	v_mov_b32_dpp v48, v0 quad_perm:[1,0,3,2] row_mask:0xf bank_mask:0xf bound_ctrl:1
	s_and_saveexec_b64 s[6:7], s[4:5]
	s_cbranch_execz .LBB0_253
	v_cvt_pk_bf16_f32 v0, v0, v48
	flat_store_dword v[14:15], v0 offset:64 nt
.LBB0_253:
	s_or_b64 exec, exec, s[6:7]
	v_mul_f32_e32 v0, v32, v80
	s_nop 1
	v_mov_b32_dpp v32, v0 quad_perm:[1,0,3,2] row_mask:0xf bank_mask:0xf bound_ctrl:1
	s_and_saveexec_b64 s[6:7], s[4:5]
	s_cbranch_execz .LBB0_255
	v_cvt_pk_bf16_f32 v0, v0, v32
	flat_store_dword v[14:15], v0 offset:128 nt
.LBB0_255:
	s_or_b64 exec, exec, s[6:7]
	v_mul_f32_e32 v0, v16, v80
	s_nop 1
	v_mov_b32_dpp v16, v0 quad_perm:[1,0,3,2] row_mask:0xf bank_mask:0xf bound_ctrl:1
	s_and_saveexec_b64 s[6:7], s[4:5]
	s_cbranch_execz .LBB0_257
	v_cvt_pk_bf16_f32 v0, v0, v16
	flat_store_dword v[14:15], v0 offset:192 nt
.LBB0_257:
	s_or_b64 exec, exec, s[6:7]
	v_rcp_f32_e32 v0, v81
	s_nop 0
	v_mul_f32_e32 v16, v65, v0
	s_nop 1
	v_mov_b32_dpp v32, v16 quad_perm:[1,0,3,2] row_mask:0xf bank_mask:0xf bound_ctrl:1
	s_and_saveexec_b64 s[6:7], s[4:5]
	s_cbranch_execz .LBB0_259
	v_cvt_pk_bf16_f32 v16, v16, v32
	flat_store_dword v[14:15], v16 offset:2048 nt
.LBB0_259:
	s_or_b64 exec, exec, s[6:7]
	v_mul_f32_e32 v16, v49, v0
	s_nop 1
	v_mov_b32_dpp v32, v16 quad_perm:[1,0,3,2] row_mask:0xf bank_mask:0xf bound_ctrl:1
	s_and_saveexec_b64 s[6:7], s[4:5]
	s_cbranch_execz .LBB0_261
	v_cvt_pk_bf16_f32 v16, v16, v32
	flat_store_dword v[14:15], v16 offset:2112 nt
.LBB0_261:
	s_or_b64 exec, exec, s[6:7]
	v_mul_f32_e32 v16, v33, v0
	s_nop 1
	v_mov_b32_dpp v32, v16 quad_perm:[1,0,3,2] row_mask:0xf bank_mask:0xf bound_ctrl:1
	s_and_saveexec_b64 s[6:7], s[4:5]
	s_cbranch_execz .LBB0_263
	v_cvt_pk_bf16_f32 v16, v16, v32
	flat_store_dword v[14:15], v16 offset:2176 nt
.LBB0_263:
	s_or_b64 exec, exec, s[6:7]
	v_mul_f32_e32 v0, v17, v0
	s_nop 1
	v_mov_b32_dpp v16, v0 quad_perm:[1,0,3,2] row_mask:0xf bank_mask:0xf bound_ctrl:1
	s_and_saveexec_b64 s[6:7], s[4:5]
	s_cbranch_execz .LBB0_265
	v_cvt_pk_bf16_f32 v0, v0, v16
	flat_store_dword v[14:15], v0 offset:2240 nt
.LBB0_265:
	s_or_b64 exec, exec, s[6:7]
	v_rcp_f32_e32 v0, v82
	s_nop 0
	v_mul_f32_e32 v16, v66, v0
	s_nop 1
	v_mov_b32_dpp v17, v16 quad_perm:[1,0,3,2] row_mask:0xf bank_mask:0xf bound_ctrl:1
	s_and_saveexec_b64 s[6:7], s[4:5]
	s_cbranch_execz .LBB0_267
	v_cvt_pk_bf16_f32 v32, v16, v17
	v_add_co_u32_e32 v16, vcc, 0x1000, v14
	s_nop 1
	v_addc_co_u32_e32 v17, vcc, 0, v15, vcc
	flat_store_dword v[16:17], v32 nt
.LBB0_267:
	s_or_b64 exec, exec, s[6:7]
	v_mul_f32_e32 v16, v50, v0
	s_nop 1
	v_mov_b32_dpp v17, v16 quad_perm:[1,0,3,2] row_mask:0xf bank_mask:0xf bound_ctrl:1
	s_and_saveexec_b64 s[6:7], s[4:5]
	s_cbranch_execz .LBB0_269
	v_cvt_pk_bf16_f32 v32, v16, v17
	v_add_co_u32_e32 v16, vcc, 0x1000, v14
	s_nop 1
	v_addc_co_u32_e32 v17, vcc, 0, v15, vcc
	flat_store_dword v[16:17], v32 offset:64 nt
.LBB0_269:
	s_or_b64 exec, exec, s[6:7]
	v_mul_f32_e32 v16, v34, v0
	s_nop 1
	v_mov_b32_dpp v17, v16 quad_perm:[1,0,3,2] row_mask:0xf bank_mask:0xf bound_ctrl:1
	s_and_saveexec_b64 s[6:7], s[4:5]
	s_cbranch_execz .LBB0_271
	v_cvt_pk_bf16_f32 v32, v16, v17
	v_add_co_u32_e32 v16, vcc, 0x1000, v14
	s_nop 1
	v_addc_co_u32_e32 v17, vcc, 0, v15, vcc
	flat_store_dword v[16:17], v32 offset:128 nt
.LBB0_271:
	s_or_b64 exec, exec, s[6:7]
	v_mul_f32_e32 v0, v18, v0
	s_nop 1
	v_mov_b32_dpp v16, v0 quad_perm:[1,0,3,2] row_mask:0xf bank_mask:0xf bound_ctrl:1
	s_and_saveexec_b64 s[6:7], s[4:5]
	s_cbranch_execz .LBB0_273
	v_cvt_pk_bf16_f32 v0, v0, v16
	v_add_co_u32_e32 v16, vcc, 0x1000, v14
	s_nop 1
	v_addc_co_u32_e32 v17, vcc, 0, v15, vcc
	flat_store_dword v[16:17], v0 offset:192 nt
.LBB0_273:
	s_or_b64 exec, exec, s[6:7]
	v_rcp_f32_e32 v0, v83
	s_nop 0
	v_mul_f32_e32 v16, v67, v0
	s_nop 1
	v_mov_b32_dpp v17, v16 quad_perm:[1,0,3,2] row_mask:0xf bank_mask:0xf bound_ctrl:1
	s_and_saveexec_b64 s[6:7], s[4:5]
	s_cbranch_execz .LBB0_275
	v_cvt_pk_bf16_f32 v18, v16, v17
	v_add_co_u32_e32 v16, vcc, 0x1000, v14
	s_nop 1
	v_addc_co_u32_e32 v17, vcc, 0, v15, vcc
	flat_store_dword v[16:17], v18 offset:2048 nt
.LBB0_275:
	s_or_b64 exec, exec, s[6:7]
	v_mul_f32_e32 v16, v51, v0
	s_nop 1
	v_mov_b32_dpp v17, v16 quad_perm:[1,0,3,2] row_mask:0xf bank_mask:0xf bound_ctrl:1
	s_and_saveexec_b64 s[6:7], s[4:5]
	s_cbranch_execz .LBB0_277
	v_cvt_pk_bf16_f32 v18, v16, v17
	v_add_co_u32_e32 v16, vcc, 0x1000, v14
	s_nop 1
	v_addc_co_u32_e32 v17, vcc, 0, v15, vcc
	flat_store_dword v[16:17], v18 offset:2112 nt
; DEVI unsigned cvtpk(float lo, float hi) { unsigned r; asm volatile("v_cvt_pk_bf16_f32 %0, %1, %2" : "=v"(r) : "v"(lo), "v"(hi)); return r; }
; template <int CTRL> DEVI float dpp(float x) { return __builtin_bit_cast(float, __builtin_amdgcn_mov_dpp(__builtin_bit_cast(int, x), CTRL, 0xf, 0xf, true)); }
; DEVI int crow(int r, int hi) { return (r & 3) + 8 * (r >> 2) + 4 * hi; }
; DEVI void block(const BlockRef& cur, const BlockRef& nxt, char* lds, Seam& S, int wv) {
;     ...
;     for (int r = 0; r < 16; ++r) { const int orow = crow(r, hi);
; #pragma unroll
;         for (int d0 = 0; d0 < 4; ++d0) { const float v = o[d0][r] * rli[r];
;             const float vn = dpp<0xB1>(v);
;             if ((r32 & 1) == 0) *(unsigned*)(Ow + (size_t)orow * RS + d0 * 32 + r32) = cvtpk(v, vn); } }
.LBB0_277:
	s_or_b64 exec, exec, s[6:7]
	v_mul_f32_e32 v16, v35, v0
	s_nop 1
	v_mov_b32_dpp v17, v16 quad_perm:[1,0,3,2] row_mask:0xf bank_mask:0xf bound_ctrl:1
	s_and_saveexec_b64 s[6:7], s[4:5]
	s_cbranch_execz .LBB0_279
	v_cvt_pk_bf16_f32 v18, v16, v17
	v_add_co_u32_e32 v16, vcc, 0x1000, v14
	s_nop 1
	v_addc_co_u32_e32 v17, vcc, 0, v15, vcc
	flat_store_dword v[16:17], v18 offset:2176 nt
.LBB0_279:
	s_or_b64 exec, exec, s[6:7]
	v_mul_f32_e32 v0, v19, v0
	s_nop 1
	v_mov_b32_dpp v16, v0 quad_perm:[1,0,3,2] row_mask:0xf bank_mask:0xf bound_ctrl:1
	s_and_saveexec_b64 s[6:7], s[4:5]
	s_cbranch_execz .LBB0_281
	v_cvt_pk_bf16_f32 v0, v0, v16
	v_add_co_u32_e32 v16, vcc, 0x1000, v14
	s_nop 1
	v_addc_co_u32_e32 v17, vcc, 0, v15, vcc
	flat_store_dword v[16:17], v0 offset:2240 nt
.LBB0_281:
	s_or_b64 exec, exec, s[6:7]
	s_waitcnt lgkmcnt(0)
	v_rcp_f32_e32 v0, v10
	s_nop 0
	v_mul_f32_e32 v10, v68, v0
	s_nop 1
	v_mov_b32_dpp v16, v10 quad_perm:[1,0,3,2] row_mask:0xf bank_mask:0xf bound_ctrl:1
	s_and_saveexec_b64 s[6:7], s[4:5]
	s_cbranch_execz .LBB0_283
	v_cvt_pk_bf16_f32 v10, v10, v16
	v_add_co_u32_e32 v16, vcc, 0x4000, v14
	s_nop 1
	v_addc_co_u32_e32 v17, vcc, 0, v15, vcc
	flat_store_dword v[16:17], v10 nt
.LBB0_283:
	s_or_b64 exec, exec, s[6:7]
	v_mul_f32_e32 v10, v52, v0
	s_nop 1
	v_mov_b32_dpp v16, v10 quad_perm:[1,0,3,2] row_mask:0xf bank_mask:0xf bound_ctrl:1
	s_and_saveexec_b64 s[6:7], s[4:5]
	s_cbranch_execz .LBB0_285
	v_cvt_pk_bf16_f32 v10, v10, v16
	v_add_co_u32_e32 v16, vcc, 0x4000, v14
	s_nop 1
	v_addc_co_u32_e32 v17, vcc, 0, v15, vcc
	flat_store_dword v[16:17], v10 offset:64 nt
.LBB0_285:
	s_or_b64 exec, exec, s[6:7]
	v_mul_f32_e32 v10, v36, v0
	s_nop 1
	v_mov_b32_dpp v16, v10 quad_perm:[1,0,3,2] row_mask:0xf bank_mask:0xf bound_ctrl:1
	s_and_saveexec_b64 s[6:7], s[4:5]
	s_cbranch_execz .LBB0_287
	v_cvt_pk_bf16_f32 v10, v10, v16
	v_add_co_u32_e32 v16, vcc, 0x4000, v14
	s_nop 1
	v_addc_co_u32_e32 v17, vcc, 0, v15, vcc
	flat_store_dword v[16:17], v10 offset:128 nt
.LBB0_287:
	s_or_b64 exec, exec, s[6:7]
	v_mul_f32_e32 v0, v20, v0
	s_nop 1
	v_mov_b32_dpp v10, v0 quad_perm:[1,0,3,2] row_mask:0xf bank_mask:0xf bound_ctrl:1
	s_and_saveexec_b64 s[6:7], s[4:5]
	s_cbranch_execz .LBB0_289
	v_add_co_u32_e32 v16, vcc, 0x4000, v14
	v_cvt_pk_bf16_f32 v0, v0, v10
	s_nop 1
	v_addc_co_u32_e32 v17, vcc, 0, v15, vcc
	flat_store_dword v[16:17], v0 offset:192 nt
.LBB0_289:
	s_or_b64 exec, exec, s[6:7]
	v_rcp_f32_e32 v0, v11
	s_nop 0
	v_mul_f32_e32 v10, v69, v0
	s_nop 1
	v_mov_b32_dpp v11, v10 quad_perm:[1,0,3,2] row_mask:0xf bank_mask:0xf bound_ctrl:1
	s_and_saveexec_b64 s[6:7], s[4:5]
	s_cbranch_execz .LBB0_291
	v_cvt_pk_bf16_f32 v16, v10, v11
	v_add_co_u32_e32 v10, vcc, 0x4000, v14
	s_nop 1
	v_addc_co_u32_e32 v11, vcc, 0, v15, vcc
	flat_store_dword v[10:11], v16 offset:2048 nt
.LBB0_291:
	s_or_b64 exec, exec, s[6:7]
	v_mul_f32_e32 v10, v53, v0
	s_nop 1
	v_mov_b32_dpp v11, v10 quad_perm:[1,0,3,2] row_mask:0xf bank_mask:0xf bound_ctrl:1
	s_and_saveexec_b64 s[6:7], s[4:5]
	s_cbranch_execz .LBB0_293
	v_cvt_pk_bf16_f32 v16, v10, v11
	v_add_co_u32_e32 v10, vcc, 0x4000, v14
	s_nop 1
	v_addc_co_u32_e32 v11, vcc, 0, v15, vcc
	flat_store_dword v[10:11], v16 offset:2112 nt
.LBB0_293:
	s_or_b64 exec, exec, s[6:7]
	v_mul_f32_e32 v10, v37, v0
	s_nop 1
	v_mov_b32_dpp v11, v10 quad_perm:[1,0,3,2] row_mask:0xf bank_mask:0xf bound_ctrl:1
	s_and_saveexec_b64 s[6:7], s[4:5]
	s_cbranch_execz .LBB0_295
	v_cvt_pk_bf16_f32 v16, v10, v11
	v_add_co_u32_e32 v10, vcc, 0x4000, v14
	s_nop 1
	v_addc_co_u32_e32 v11, vcc, 0, v15, vcc
	flat_store_dword v[10:11], v16 offset:2176 nt
.LBB0_295:
	s_or_b64 exec, exec, s[6:7]
	v_mul_f32_e32 v0, v21, v0
	s_nop 1
	v_mov_b32_dpp v10, v0 quad_perm:[1,0,3,2] row_mask:0xf bank_mask:0xf bound_ctrl:1
	s_and_saveexec_b64 s[6:7], s[4:5]
	s_cbranch_execz .LBB0_297
	v_cvt_pk_bf16_f32 v0, v0, v10
	v_add_co_u32_e32 v10, vcc, 0x4000, v14
	s_nop 1
	v_addc_co_u32_e32 v11, vcc, 0, v15, vcc
	flat_store_dword v[10:11], v0 offset:2240 nt
.LBB0_297:
	s_or_b64 exec, exec, s[6:7]
	v_rcp_f32_e32 v0, v12
	s_nop 0
	v_mul_f32_e32 v10, v70, v0
	s_nop 1
	v_mov_b32_dpp v11, v10 quad_perm:[1,0,3,2] row_mask:0xf bank_mask:0xf bound_ctrl:1
	s_and_saveexec_b64 s[6:7], s[4:5]
	s_cbranch_execz .LBB0_299
	v_cvt_pk_bf16_f32 v12, v10, v11
	v_add_co_u32_e32 v10, vcc, 0x5000, v14
	s_nop 1
	v_addc_co_u32_e32 v11, vcc, 0, v15, vcc
	flat_store_dword v[10:11], v12 nt
.LBB0_299:
	s_or_b64 exec, exec, s[6:7]
	v_mul_f32_e32 v10, v54, v0
	s_nop 1
	v_mov_b32_dpp v11, v10 quad_perm:[1,0,3,2] row_mask:0xf bank_mask:0xf bound_ctrl:1
	s_and_saveexec_b64 s[6:7], s[4:5]
	s_cbranch_execz .LBB0_301
	v_cvt_pk_bf16_f32 v12, v10, v11
	v_add_co_u32_e32 v10, vcc, 0x5000, v14
	s_nop 1
	v_addc_co_u32_e32 v11, vcc, 0, v15, vcc
	flat_store_dword v[10:11], v12 offset:64 nt
.LBB0_301:
	s_or_b64 exec, exec, s[6:7]
	v_mul_f32_e32 v10, v38, v0
	s_nop 1
	v_mov_b32_dpp v11, v10 quad_perm:[1,0,3,2] row_mask:0xf bank_mask:0xf bound_ctrl:1
	s_and_saveexec_b64 s[6:7], s[4:5]
	s_cbranch_execz .LBB0_303
	v_cvt_pk_bf16_f32 v12, v10, v11
	v_add_co_u32_e32 v10, vcc, 0x5000, v14
	s_nop 1
	v_addc_co_u32_e32 v11, vcc, 0, v15, vcc
	flat_store_dword v[10:11], v12 offset:128 nt
.LBB0_303:
	s_or_b64 exec, exec, s[6:7]
	v_mul_f32_e32 v0, v22, v0
	s_nop 1
	v_mov_b32_dpp v10, v0 quad_perm:[1,0,3,2] row_mask:0xf bank_mask:0xf bound_ctrl:1
	s_and_saveexec_b64 s[6:7], s[4:5]
	s_cbranch_execz .LBB0_305
	v_cvt_pk_bf16_f32 v0, v0, v10
	v_add_co_u32_e32 v10, vcc, 0x5000, v14
	s_nop 1
	v_addc_co_u32_e32 v11, vcc, 0, v15, vcc
	flat_store_dword v[10:11], v0 offset:192 nt
; DEVI unsigned cvtpk(float lo, float hi) { unsigned r; asm volatile("v_cvt_pk_bf16_f32 %0, %1, %2" : "=v"(r) : "v"(lo), "v"(hi)); return r; }
; template <int CTRL> DEVI float dpp(float x) { return __builtin_bit_cast(float, __builtin_amdgcn_mov_dpp(__builtin_bit_cast(int, x), CTRL, 0xf, 0xf, true)); }
; DEVI int crow(int r, int hi) { return (r & 3) + 8 * (r >> 2) + 4 * hi; }
; DEVI void block(const BlockRef& cur, const BlockRef& nxt, char* lds, Seam& S, int wv) {
;     ...
;     for (int r = 0; r < 16; ++r) { const int orow = crow(r, hi);
; #pragma unroll
;         for (int d0 = 0; d0 < 4; ++d0) { const float v = o[d0][r] * rli[r];
;             const float vn = dpp<0xB1>(v);
;             if ((r32 & 1) == 0) *(unsigned*)(Ow + (size_t)orow * RS + d0 * 32 + r32) = cvtpk(v, vn); } }
.LBB0_305:
	s_or_b64 exec, exec, s[6:7]
	v_rcp_f32_e32 v0, v13
	s_nop 0
	v_mul_f32_e32 v10, v71, v0
	s_nop 1
	v_mov_b32_dpp v11, v10 quad_perm:[1,0,3,2] row_mask:0xf bank_mask:0xf bound_ctrl:1
	s_and_saveexec_b64 s[6:7], s[4:5]
	s_cbranch_execz .LBB0_307
	v_cvt_pk_bf16_f32 v12, v10, v11
	v_add_co_u32_e32 v10, vcc, 0x5000, v14
	s_nop 1
	v_addc_co_u32_e32 v11, vcc, 0, v15, vcc
	flat_store_dword v[10:11], v12 offset:2048 nt
.LBB0_307:
	s_or_b64 exec, exec, s[6:7]
	v_mul_f32_e32 v10, v55, v0
	s_nop 1
	v_mov_b32_dpp v11, v10 quad_perm:[1,0,3,2] row_mask:0xf bank_mask:0xf bound_ctrl:1
	s_and_saveexec_b64 s[6:7], s[4:5]
	s_cbranch_execz .LBB0_309
	v_cvt_pk_bf16_f32 v12, v10, v11
	v_add_co_u32_e32 v10, vcc, 0x5000, v14
	s_nop 1
	v_addc_co_u32_e32 v11, vcc, 0, v15, vcc
	flat_store_dword v[10:11], v12 offset:2112 nt
.LBB0_309:
	s_or_b64 exec, exec, s[6:7]
	v_mul_f32_e32 v10, v39, v0
	s_nop 1
	v_mov_b32_dpp v11, v10 quad_perm:[1,0,3,2] row_mask:0xf bank_mask:0xf bound_ctrl:1
	s_and_saveexec_b64 s[6:7], s[4:5]
	s_cbranch_execz .LBB0_311
	v_cvt_pk_bf16_f32 v12, v10, v11
	v_add_co_u32_e32 v10, vcc, 0x5000, v14
	s_nop 1
	v_addc_co_u32_e32 v11, vcc, 0, v15, vcc
	flat_store_dword v[10:11], v12 offset:2176 nt
.LBB0_311:
	s_or_b64 exec, exec, s[6:7]
	v_mul_f32_e32 v0, v23, v0
	s_nop 1
	v_mov_b32_dpp v10, v0 quad_perm:[1,0,3,2] row_mask:0xf bank_mask:0xf bound_ctrl:1
	s_and_saveexec_b64 s[6:7], s[4:5]
	s_cbranch_execz .LBB0_313
	v_cvt_pk_bf16_f32 v0, v0, v10
	v_add_co_u32_e32 v10, vcc, 0x5000, v14
	s_nop 1
	v_addc_co_u32_e32 v11, vcc, 0, v15, vcc
	flat_store_dword v[10:11], v0 offset:2240 nt
.LBB0_313:
	s_or_b64 exec, exec, s[6:7]
	v_rcp_f32_e32 v0, v6
	s_nop 0
	v_mul_f32_e32 v6, v72, v0
	s_nop 1
	v_mov_b32_dpp v10, v6 quad_perm:[1,0,3,2] row_mask:0xf bank_mask:0xf bound_ctrl:1
	s_and_saveexec_b64 s[6:7], s[4:5]
	s_cbranch_execz .LBB0_315
	v_cvt_pk_bf16_f32 v6, v6, v10
	v_add_co_u32_e32 v10, vcc, 0x8000, v14
	s_nop 1
	v_addc_co_u32_e32 v11, vcc, 0, v15, vcc
	flat_store_dword v[10:11], v6 nt
.LBB0_315:
	s_or_b64 exec, exec, s[6:7]
	v_mul_f32_e32 v6, v56, v0
	s_nop 1
	v_mov_b32_dpp v10, v6 quad_perm:[1,0,3,2] row_mask:0xf bank_mask:0xf bound_ctrl:1
	s_and_saveexec_b64 s[6:7], s[4:5]
	s_cbranch_execz .LBB0_317
	v_cvt_pk_bf16_f32 v6, v6, v10
	v_add_co_u32_e32 v10, vcc, 0x8000, v14
	s_nop 1
	v_addc_co_u32_e32 v11, vcc, 0, v15, vcc
	flat_store_dword v[10:11], v6 offset:64 nt
.LBB0_317:
	s_or_b64 exec, exec, s[6:7]
	v_mul_f32_e32 v6, v40, v0
	s_nop 1
	v_mov_b32_dpp v10, v6 quad_perm:[1,0,3,2] row_mask:0xf bank_mask:0xf bound_ctrl:1
	s_and_saveexec_b64 s[6:7], s[4:5]
	s_cbranch_execz .LBB0_319
	v_cvt_pk_bf16_f32 v6, v6, v10
	v_add_co_u32_e32 v10, vcc, 0x8000, v14
	s_nop 1
	v_addc_co_u32_e32 v11, vcc, 0, v15, vcc
	flat_store_dword v[10:11], v6 offset:128 nt
.LBB0_319:
	s_or_b64 exec, exec, s[6:7]
	v_mul_f32_e32 v0, v24, v0
	s_nop 1
	v_mov_b32_dpp v6, v0 quad_perm:[1,0,3,2] row_mask:0xf bank_mask:0xf bound_ctrl:1
	s_and_saveexec_b64 s[6:7], s[4:5]
	s_cbranch_execz .LBB0_321
	v_add_co_u32_e32 v10, vcc, 0x8000, v14
	v_cvt_pk_bf16_f32 v0, v0, v6
	s_nop 1
	v_addc_co_u32_e32 v11, vcc, 0, v15, vcc
	flat_store_dword v[10:11], v0 offset:192 nt
.LBB0_321:
	s_or_b64 exec, exec, s[6:7]
	v_rcp_f32_e32 v0, v7
	s_nop 0
	v_mul_f32_e32 v6, v73, v0
	s_nop 1
	v_mov_b32_dpp v7, v6 quad_perm:[1,0,3,2] row_mask:0xf bank_mask:0xf bound_ctrl:1
	s_and_saveexec_b64 s[6:7], s[4:5]
	s_cbranch_execz .LBB0_323
	v_cvt_pk_bf16_f32 v10, v6, v7
	v_add_co_u32_e32 v6, vcc, 0x8000, v14
	s_nop 1
	v_addc_co_u32_e32 v7, vcc, 0, v15, vcc
	flat_store_dword v[6:7], v10 offset:2048 nt
.LBB0_323:
	s_or_b64 exec, exec, s[6:7]
	v_mul_f32_e32 v6, v57, v0
	s_nop 1
	v_mov_b32_dpp v7, v6 quad_perm:[1,0,3,2] row_mask:0xf bank_mask:0xf bound_ctrl:1
	s_and_saveexec_b64 s[6:7], s[4:5]
	s_cbranch_execz .LBB0_325
	v_cvt_pk_bf16_f32 v10, v6, v7
	v_add_co_u32_e32 v6, vcc, 0x8000, v14
	s_nop 1
	v_addc_co_u32_e32 v7, vcc, 0, v15, vcc
	flat_store_dword v[6:7], v10 offset:2112 nt
.LBB0_325:
	s_or_b64 exec, exec, s[6:7]
	v_mul_f32_e32 v6, v41, v0
	s_nop 1
	v_mov_b32_dpp v7, v6 quad_perm:[1,0,3,2] row_mask:0xf bank_mask:0xf bound_ctrl:1
	s_and_saveexec_b64 s[6:7], s[4:5]
	s_cbranch_execz .LBB0_327
	v_cvt_pk_bf16_f32 v10, v6, v7
	v_add_co_u32_e32 v6, vcc, 0x8000, v14
	s_nop 1
	v_addc_co_u32_e32 v7, vcc, 0, v15, vcc
	flat_store_dword v[6:7], v10 offset:2176 nt
.LBB0_327:
	s_or_b64 exec, exec, s[6:7]
	v_mul_f32_e32 v0, v25, v0
	s_nop 1
	v_mov_b32_dpp v6, v0 quad_perm:[1,0,3,2] row_mask:0xf bank_mask:0xf bound_ctrl:1
	s_and_saveexec_b64 s[6:7], s[4:5]
	s_cbranch_execz .LBB0_329
	v_cvt_pk_bf16_f32 v0, v0, v6
	v_add_co_u32_e32 v6, vcc, 0x8000, v14
	s_nop 1
	v_addc_co_u32_e32 v7, vcc, 0, v15, vcc
	flat_store_dword v[6:7], v0 offset:2240 nt
.LBB0_329:
	s_or_b64 exec, exec, s[6:7]
	v_rcp_f32_e32 v0, v8
	s_nop 0
	v_mul_f32_e32 v6, v74, v0
	s_nop 1
	v_mov_b32_dpp v7, v6 quad_perm:[1,0,3,2] row_mask:0xf bank_mask:0xf bound_ctrl:1
	s_and_saveexec_b64 s[6:7], s[4:5]
	s_cbranch_execz .LBB0_331
	v_cvt_pk_bf16_f32 v8, v6, v7
	v_add_co_u32_e32 v6, vcc, 0x9000, v14
	s_nop 1
	v_addc_co_u32_e32 v7, vcc, 0, v15, vcc
	flat_store_dword v[6:7], v8 nt
.LBB0_331:
	s_or_b64 exec, exec, s[6:7]
	v_mul_f32_e32 v6, v58, v0
	s_nop 1
	v_mov_b32_dpp v7, v6 quad_perm:[1,0,3,2] row_mask:0xf bank_mask:0xf bound_ctrl:1
	s_and_saveexec_b64 s[6:7], s[4:5]
	s_cbranch_execz .LBB0_333
	v_cvt_pk_bf16_f32 v8, v6, v7
	v_add_co_u32_e32 v6, vcc, 0x9000, v14
	s_nop 1
	v_addc_co_u32_e32 v7, vcc, 0, v15, vcc
	flat_store_dword v[6:7], v8 offset:64 nt
; DEVI unsigned cvtpk(float lo, float hi) { unsigned r; asm volatile("v_cvt_pk_bf16_f32 %0, %1, %2" : "=v"(r) : "v"(lo), "v"(hi)); return r; }
; template <int CTRL> DEVI float dpp(float x) { return __builtin_bit_cast(float, __builtin_amdgcn_mov_dpp(__builtin_bit_cast(int, x), CTRL, 0xf, 0xf, true)); }
; DEVI int crow(int r, int hi) { return (r & 3) + 8 * (r >> 2) + 4 * hi; }
; DEVI void block(const BlockRef& cur, const BlockRef& nxt, char* lds, Seam& S, int wv) {
;     ...
;     for (int r = 0; r < 16; ++r) { const int orow = crow(r, hi);
; #pragma unroll
;         for (int d0 = 0; d0 < 4; ++d0) { const float v = o[d0][r] * rli[r];
;             const float vn = dpp<0xB1>(v);
;             if ((r32 & 1) == 0) *(unsigned*)(Ow + (size_t)orow * RS + d0 * 32 + r32) = cvtpk(v, vn); } }
.LBB0_333:
	s_or_b64 exec, exec, s[6:7]
	v_mul_f32_e32 v6, v42, v0
	s_nop 1
	v_mov_b32_dpp v7, v6 quad_perm:[1,0,3,2] row_mask:0xf bank_mask:0xf bound_ctrl:1
	s_and_saveexec_b64 s[6:7], s[4:5]
	s_cbranch_execz .LBB0_335
	v_cvt_pk_bf16_f32 v8, v6, v7
	v_add_co_u32_e32 v6, vcc, 0x9000, v14
	s_nop 1
	v_addc_co_u32_e32 v7, vcc, 0, v15, vcc
	flat_store_dword v[6:7], v8 offset:128 nt
.LBB0_335:
	s_or_b64 exec, exec, s[6:7]
	v_mul_f32_e32 v0, v26, v0
	s_nop 1
	v_mov_b32_dpp v6, v0 quad_perm:[1,0,3,2] row_mask:0xf bank_mask:0xf bound_ctrl:1
	s_and_saveexec_b64 s[6:7], s[4:5]
	s_cbranch_execz .LBB0_337
	v_cvt_pk_bf16_f32 v0, v0, v6
	v_add_co_u32_e32 v6, vcc, 0x9000, v14
	s_nop 1
	v_addc_co_u32_e32 v7, vcc, 0, v15, vcc
	flat_store_dword v[6:7], v0 offset:192 nt
.LBB0_337:
	s_or_b64 exec, exec, s[6:7]
	v_rcp_f32_e32 v0, v9
	s_nop 0
	v_mul_f32_e32 v6, v75, v0
	s_nop 1
	v_mov_b32_dpp v7, v6 quad_perm:[1,0,3,2] row_mask:0xf bank_mask:0xf bound_ctrl:1
	s_and_saveexec_b64 s[6:7], s[4:5]
	s_cbranch_execz .LBB0_339
	v_cvt_pk_bf16_f32 v8, v6, v7
	v_add_co_u32_e32 v6, vcc, 0x9000, v14
	s_nop 1
	v_addc_co_u32_e32 v7, vcc, 0, v15, vcc
	flat_store_dword v[6:7], v8 offset:2048 nt
.LBB0_339:
	s_or_b64 exec, exec, s[6:7]
	v_mul_f32_e32 v6, v59, v0
	s_nop 1
	v_mov_b32_dpp v7, v6 quad_perm:[1,0,3,2] row_mask:0xf bank_mask:0xf bound_ctrl:1
	s_and_saveexec_b64 s[6:7], s[4:5]
	s_cbranch_execz .LBB0_341
	v_cvt_pk_bf16_f32 v8, v6, v7
	v_add_co_u32_e32 v6, vcc, 0x9000, v14
	s_nop 1
	v_addc_co_u32_e32 v7, vcc, 0, v15, vcc
	flat_store_dword v[6:7], v8 offset:2112 nt
.LBB0_341:
	s_or_b64 exec, exec, s[6:7]
	v_mul_f32_e32 v6, v43, v0
	s_nop 1
	v_mov_b32_dpp v7, v6 quad_perm:[1,0,3,2] row_mask:0xf bank_mask:0xf bound_ctrl:1
	s_and_saveexec_b64 s[6:7], s[4:5]
	s_cbranch_execz .LBB0_343
	v_cvt_pk_bf16_f32 v8, v6, v7
	v_add_co_u32_e32 v6, vcc, 0x9000, v14
	s_nop 1
	v_addc_co_u32_e32 v7, vcc, 0, v15, vcc
	flat_store_dword v[6:7], v8 offset:2176 nt
.LBB0_343:
	s_or_b64 exec, exec, s[6:7]
	v_mul_f32_e32 v0, v27, v0
	s_nop 1
	v_mov_b32_dpp v6, v0 quad_perm:[1,0,3,2] row_mask:0xf bank_mask:0xf bound_ctrl:1
	s_and_saveexec_b64 s[6:7], s[4:5]
	s_cbranch_execz .LBB0_345
	v_cvt_pk_bf16_f32 v0, v0, v6
	v_add_co_u32_e32 v6, vcc, 0x9000, v14
	s_nop 1
	v_addc_co_u32_e32 v7, vcc, 0, v15, vcc
	flat_store_dword v[6:7], v0 offset:2240 nt
.LBB0_345:
	s_or_b64 exec, exec, s[6:7]
	v_rcp_f32_e32 v0, v2
	s_nop 0
	v_mul_f32_e32 v2, v76, v0
	s_nop 1
	v_mov_b32_dpp v6, v2 quad_perm:[1,0,3,2] row_mask:0xf bank_mask:0xf bound_ctrl:1
	s_and_saveexec_b64 s[6:7], s[4:5]
	s_cbranch_execz .LBB0_347
	v_cvt_pk_bf16_f32 v2, v2, v6
	v_add_co_u32_e32 v6, vcc, 0xc000, v14
	s_nop 1
	v_addc_co_u32_e32 v7, vcc, 0, v15, vcc
	flat_store_dword v[6:7], v2 nt
.LBB0_347:
	s_or_b64 exec, exec, s[6:7]
	v_mul_f32_e32 v2, v60, v0
	s_nop 1
	v_mov_b32_dpp v6, v2 quad_perm:[1,0,3,2] row_mask:0xf bank_mask:0xf bound_ctrl:1
	s_and_saveexec_b64 s[6:7], s[4:5]
	s_cbranch_execz .LBB0_349
	v_cvt_pk_bf16_f32 v2, v2, v6
	v_add_co_u32_e32 v6, vcc, 0xc000, v14
	s_nop 1
	v_addc_co_u32_e32 v7, vcc, 0, v15, vcc
	flat_store_dword v[6:7], v2 offset:64 nt
.LBB0_349:
	s_or_b64 exec, exec, s[6:7]
	v_mul_f32_e32 v2, v44, v0
	s_nop 1
	v_mov_b32_dpp v6, v2 quad_perm:[1,0,3,2] row_mask:0xf bank_mask:0xf bound_ctrl:1
	s_and_saveexec_b64 s[6:7], s[4:5]
	s_cbranch_execz .LBB0_351
	v_cvt_pk_bf16_f32 v2, v2, v6
	v_add_co_u32_e32 v6, vcc, 0xc000, v14
	s_nop 1
	v_addc_co_u32_e32 v7, vcc, 0, v15, vcc
	flat_store_dword v[6:7], v2 offset:128 nt
.LBB0_351:
	s_or_b64 exec, exec, s[6:7]
	v_mul_f32_e32 v0, v28, v0
	s_nop 1
	v_mov_b32_dpp v2, v0 quad_perm:[1,0,3,2] row_mask:0xf bank_mask:0xf bound_ctrl:1
	s_and_saveexec_b64 s[6:7], s[4:5]
	s_cbranch_execz .LBB0_353
	v_add_co_u32_e32 v6, vcc, 0xc000, v14
	v_cvt_pk_bf16_f32 v0, v0, v2
	s_nop 1
	v_addc_co_u32_e32 v7, vcc, 0, v15, vcc
	flat_store_dword v[6:7], v0 offset:192 nt
.LBB0_353:
	s_or_b64 exec, exec, s[6:7]
	v_rcp_f32_e32 v0, v3
	s_nop 0
	v_mul_f32_e32 v2, v77, v0
	s_nop 1
	v_mov_b32_dpp v3, v2 quad_perm:[1,0,3,2] row_mask:0xf bank_mask:0xf bound_ctrl:1
	s_and_saveexec_b64 s[6:7], s[4:5]
	s_cbranch_execz .LBB0_355
	v_cvt_pk_bf16_f32 v6, v2, v3
	v_add_co_u32_e32 v2, vcc, 0xc000, v14
	s_nop 1
	v_addc_co_u32_e32 v3, vcc, 0, v15, vcc
	flat_store_dword v[2:3], v6 offset:2048 nt
; DEVI unsigned cvtpk(float lo, float hi) { unsigned r; asm volatile("v_cvt_pk_bf16_f32 %0, %1, %2" : "=v"(r) : "v"(lo), "v"(hi)); return r; }
; template <int CTRL> DEVI float dpp(float x) { return __builtin_bit_cast(float, __builtin_amdgcn_mov_dpp(__builtin_bit_cast(int, x), CTRL, 0xf, 0xf, true)); }
; DEVI int crow(int r, int hi) { return (r & 3) + 8 * (r >> 2) + 4 * hi; }
; DEVI void block(const BlockRef& cur, const BlockRef& nxt, char* lds, Seam& S, int wv) {
;     ...
;     for (int r = 0; r < 16; ++r) { const int orow = crow(r, hi);
; #pragma unroll
;         for (int d0 = 0; d0 < 4; ++d0) { const float v = o[d0][r] * rli[r];
;             const float vn = dpp<0xB1>(v);
;             if ((r32 & 1) == 0) *(unsigned*)(Ow + (size_t)orow * RS + d0 * 32 + r32) = cvtpk(v, vn); } }
.LBB0_355:
	s_or_b64 exec, exec, s[6:7]
	v_mul_f32_e32 v2, v61, v0
	s_nop 1
	v_mov_b32_dpp v3, v2 quad_perm:[1,0,3,2] row_mask:0xf bank_mask:0xf bound_ctrl:1
	s_and_saveexec_b64 s[6:7], s[4:5]
	s_cbranch_execz .LBB0_357
	v_cvt_pk_bf16_f32 v6, v2, v3
	v_add_co_u32_e32 v2, vcc, 0xc000, v14
	s_nop 1
	v_addc_co_u32_e32 v3, vcc, 0, v15, vcc
	flat_store_dword v[2:3], v6 offset:2112 nt
.LBB0_357:
	s_or_b64 exec, exec, s[6:7]
	v_mul_f32_e32 v2, v45, v0
	s_nop 1
	v_mov_b32_dpp v3, v2 quad_perm:[1,0,3,2] row_mask:0xf bank_mask:0xf bound_ctrl:1
	s_and_saveexec_b64 s[6:7], s[4:5]
	s_cbranch_execz .LBB0_359
	v_cvt_pk_bf16_f32 v6, v2, v3
	v_add_co_u32_e32 v2, vcc, 0xc000, v14
	s_nop 1
	v_addc_co_u32_e32 v3, vcc, 0, v15, vcc
	flat_store_dword v[2:3], v6 offset:2176 nt
.LBB0_359:
	s_or_b64 exec, exec, s[6:7]
	v_mul_f32_e32 v0, v29, v0
	s_nop 1
	v_mov_b32_dpp v2, v0 quad_perm:[1,0,3,2] row_mask:0xf bank_mask:0xf bound_ctrl:1
	s_and_saveexec_b64 s[6:7], s[4:5]
	s_cbranch_execz .LBB0_361
	v_cvt_pk_bf16_f32 v0, v0, v2
	v_add_co_u32_e32 v2, vcc, 0xc000, v14
	s_nop 1
	v_addc_co_u32_e32 v3, vcc, 0, v15, vcc
	flat_store_dword v[2:3], v0 offset:2240 nt
.LBB0_361:
	s_or_b64 exec, exec, s[6:7]
	v_rcp_f32_e32 v0, v4
	s_nop 0
	v_mul_f32_e32 v2, v78, v0
	s_nop 1
	v_mov_b32_dpp v3, v2 quad_perm:[1,0,3,2] row_mask:0xf bank_mask:0xf bound_ctrl:1
	s_and_saveexec_b64 s[6:7], s[4:5]
	s_cbranch_execz .LBB0_363
	v_cvt_pk_bf16_f32 v4, v2, v3
	v_add_co_u32_e32 v2, vcc, 0xd000, v14
	s_nop 1
	v_addc_co_u32_e32 v3, vcc, 0, v15, vcc
	flat_store_dword v[2:3], v4 nt
.LBB0_363:
	s_or_b64 exec, exec, s[6:7]
	v_mul_f32_e32 v2, v62, v0
	s_nop 1
	v_mov_b32_dpp v3, v2 quad_perm:[1,0,3,2] row_mask:0xf bank_mask:0xf bound_ctrl:1
	s_and_saveexec_b64 s[6:7], s[4:5]
	s_cbranch_execz .LBB0_365
	v_cvt_pk_bf16_f32 v4, v2, v3
	v_add_co_u32_e32 v2, vcc, 0xd000, v14
	s_nop 1
	v_addc_co_u32_e32 v3, vcc, 0, v15, vcc
	flat_store_dword v[2:3], v4 offset:64 nt
.LBB0_365:
	s_or_b64 exec, exec, s[6:7]
	v_mul_f32_e32 v2, v46, v0
	s_nop 1
	v_mov_b32_dpp v3, v2 quad_perm:[1,0,3,2] row_mask:0xf bank_mask:0xf bound_ctrl:1
	s_and_saveexec_b64 s[6:7], s[4:5]
	s_cbranch_execz .LBB0_367
	v_cvt_pk_bf16_f32 v4, v2, v3
	v_add_co_u32_e32 v2, vcc, 0xd000, v14
	s_nop 1
	v_addc_co_u32_e32 v3, vcc, 0, v15, vcc
	flat_store_dword v[2:3], v4 offset:128 nt
.LBB0_367:
	s_or_b64 exec, exec, s[6:7]
	v_mul_f32_e32 v0, v30, v0
	s_nop 1
	v_mov_b32_dpp v2, v0 quad_perm:[1,0,3,2] row_mask:0xf bank_mask:0xf bound_ctrl:1
	s_and_saveexec_b64 s[6:7], s[4:5]
	s_cbranch_execz .LBB0_369
	v_cvt_pk_bf16_f32 v0, v0, v2
	v_add_co_u32_e32 v2, vcc, 0xd000, v14
	s_nop 1
	v_addc_co_u32_e32 v3, vcc, 0, v15, vcc
	flat_store_dword v[2:3], v0 offset:192 nt
.LBB0_369:
	s_or_b64 exec, exec, s[6:7]
	v_rcp_f32_e32 v0, v5
	s_nop 0
	v_mul_f32_e32 v2, v79, v0
	s_nop 1
	v_mov_b32_dpp v3, v2 quad_perm:[1,0,3,2] row_mask:0xf bank_mask:0xf bound_ctrl:1
	s_and_saveexec_b64 s[6:7], s[4:5]
	s_cbranch_execz .LBB0_371
	v_cvt_pk_bf16_f32 v4, v2, v3
	v_add_co_u32_e32 v2, vcc, 0xd000, v14
	s_nop 1
	v_addc_co_u32_e32 v3, vcc, 0, v15, vcc
	flat_store_dword v[2:3], v4 offset:2048 nt
.LBB0_371:
	s_or_b64 exec, exec, s[6:7]
	v_mul_f32_e32 v2, v63, v0
	s_nop 1
	v_mov_b32_dpp v3, v2 quad_perm:[1,0,3,2] row_mask:0xf bank_mask:0xf bound_ctrl:1
	s_and_saveexec_b64 s[6:7], s[4:5]
	s_cbranch_execz .LBB0_373
	v_cvt_pk_bf16_f32 v4, v2, v3
	v_add_co_u32_e32 v2, vcc, 0xd000, v14
	s_nop 1
	v_addc_co_u32_e32 v3, vcc, 0, v15, vcc
	flat_store_dword v[2:3], v4 offset:2112 nt
.LBB0_373:
	s_or_b64 exec, exec, s[6:7]
	v_mul_f32_e32 v2, v47, v0
	s_nop 1
	v_mov_b32_dpp v3, v2 quad_perm:[1,0,3,2] row_mask:0xf bank_mask:0xf bound_ctrl:1
	s_and_saveexec_b64 s[6:7], s[4:5]
	s_cbranch_execz .LBB0_375
	v_cvt_pk_bf16_f32 v4, v2, v3
	v_add_co_u32_e32 v2, vcc, 0xd000, v14
	s_nop 1
	v_addc_co_u32_e32 v3, vcc, 0, v15, vcc
	flat_store_dword v[2:3], v4 offset:2176 nt
.LBB0_375:
	s_or_b64 exec, exec, s[6:7]
	v_mul_f32_e32 v0, v31, v0
	s_nop 1
	v_mov_b32_dpp v2, v0 quad_perm:[1,0,3,2] row_mask:0xf bank_mask:0xf bound_ctrl:1
	s_and_saveexec_b64 s[6:7], s[4:5]
	s_cbranch_execz .LBB0_201
	v_cvt_pk_bf16_f32 v0, v0, v2
	v_add_co_u32_e32 v2, vcc, 0xd000, v14
	s_nop 1
	v_addc_co_u32_e32 v3, vcc, 0, v15, vcc
	flat_store_dword v[2:3], v0 offset:2240 nt
	s_branch .LBB0_201
